# fp8 attention steps (no-mask variants): 8-input row max as 3x v_max3 + 1x v_max instead of the compiler's 11-op canonicalizing tree
# speedup vs baseline: 1.0015x; 1.0015x over previous
; template <bool SLC, bool NOMASK> ...
;     ...
;     if (NOMASK) {
; #pragma unroll
;         for (int j = 0; j < 8; ++j) { sc[j] = sa[j >> 2][j & 3]; vd[j] = act; }
;         mx = fmaxf(fmaxf(fmaxf(sc[0], sc[1]), fmaxf(sc[2], sc[3])), fmaxf(fmaxf(sc[4], sc[5]), fmaxf(sc[6], sc[7])));
;         mx = act ? mx : -1e30f;
;     ...
;     if (__builtin_amdgcn_ballot_w64(mx > st.m + 4.f) != 0ull) {
;         mx = fmaxf(mx, __shfl_xor(mx, 16)); mx = fmaxf(mx, __shfl_xor(mx, 32));
;         const float mn = fmaxf(st.m, mx), alpha = __builtin_amdgcn_exp2f(st.m - mn); st.m = mn; st.l *= alpha;
; #pragma unroll
;         for (int j = 0; j < 8; ++j) st.o[j] = st.o[j] * alpha;
;     }
.LBB0_704:
	v_lshl_add_u64 v[244:245], v[198:199], 0, v[98:99]
	global_load_dwordx4 v[180:183], v[244:245], off
	global_load_dwordx4 v[184:187], v[244:245], off offset:1024
	global_load_dwordx4 v[188:191], v[244:245], off offset:2048
	global_load_dwordx4 v[192:195], v[244:245], off offset:3072
	v_lshl_add_u64 v[246:247], v[196:197], 0, v[98:99]
	global_load_dwordx4 v[164:167], v[246:247], off
	global_load_dwordx4 v[168:171], v[246:247], off offset:1024
	global_load_dwordx4 v[172:175], v[246:247], off offset:2048
	global_load_dwordx4 v[176:179], v[246:247], off offset:3072
	s_waitcnt vmcnt(20)
	v_mfma_f32_16x16x128_f8f6f4 v[2:5], v[132:139], v[74:81], 0
	v_mfma_f32_16x16x128_f8f6f4 v[6:9], v[140:147], v[74:81], 0
	v_mov_b32_e32 v207, v210
	v_mov_b32_e32 v208, v209
	s_nop 8
	v_max3_f32 v0, v2, v3, v4
	v_max3_f32 v12, v5, v6, v7
	v_max3_f32 v0, v0, v8, v9
	v_max_f32_e32 v0, v0, v12
	v_cmp_gt_f32_e32 vcc, v0, v211
	s_cbranch_vccz .LBB0_706
	v_and_b32_e32 v11, 64, v204
	v_xor_b32_e32 v10, 16, v204
	v_add_u32_e32 v11, 64, v11
	v_cmp_lt_i32_e32 vcc, v10, v11
	v_xor_b32_e32 v12, 32, v204
	s_nop 0
	v_cndmask_b32_e32 v10, v204, v10, vcc
	v_lshlrev_b32_e32 v10, 2, v10
	ds_bpermute_b32 v10, v10, v0
	v_max_f32_e32 v0, v0, v0
	v_cmp_lt_i32_e32 vcc, v12, v11
	s_waitcnt lgkmcnt(0)
	v_max_f32_e32 v10, v10, v10
	v_max_f32_e32 v0, v0, v10
	v_cndmask_b32_e32 v10, v204, v12, vcc
	v_lshlrev_b32_e32 v10, 2, v10
	ds_bpermute_b32 v10, v10, v0
	s_waitcnt lgkmcnt(0)
	v_max3_f32 v207, v210, v0, v10
	v_sub_f32_e32 v0, v210, v207
	v_exp_f32_e32 v0, v0
	s_nop 0
	v_mul_f32_e32 v208, v209, v0
	v_pk_mul_f32 v[36:37], v[36:37], v[0:1] op_sel_hi:[1,0]
	v_pk_mul_f32 v[34:35], v[34:35], v[0:1] op_sel_hi:[1,0]
	v_pk_mul_f32 v[40:41], v[40:41], v[0:1] op_sel_hi:[1,0]
	v_pk_mul_f32 v[38:39], v[38:39], v[0:1] op_sel_hi:[1,0]
	v_pk_mul_f32 v[44:45], v[44:45], v[0:1] op_sel_hi:[1,0]
	v_pk_mul_f32 v[42:43], v[42:43], v[0:1] op_sel_hi:[1,0]
	v_pk_mul_f32 v[56:57], v[56:57], v[0:1] op_sel_hi:[1,0]
	v_pk_mul_f32 v[54:55], v[54:55], v[0:1] op_sel_hi:[1,0]
	v_pk_mul_f32 v[64:65], v[64:65], v[0:1] op_sel_hi:[1,0]
	v_pk_mul_f32 v[62:63], v[62:63], v[0:1] op_sel_hi:[1,0]
	v_pk_mul_f32 v[60:61], v[60:61], v[0:1] op_sel_hi:[1,0]
	v_pk_mul_f32 v[58:59], v[58:59], v[0:1] op_sel_hi:[1,0]
	v_pk_mul_f32 v[52:53], v[52:53], v[0:1] op_sel_hi:[1,0]
	v_pk_mul_f32 v[50:51], v[50:51], v[0:1] op_sel_hi:[1,0]
	v_pk_mul_f32 v[48:49], v[48:49], v[0:1] op_sel_hi:[1,0]
	v_pk_mul_f32 v[46:47], v[46:47], v[0:1] op_sel_hi:[1,0]

; template <bool SLC, bool NOMASK> ...
;     ...
;     if (NOMASK) {
; #pragma unroll
;         for (int j = 0; j < 8; ++j) { sc[j] = sa[j >> 2][j & 3]; vd[j] = act; }
;         mx = fmaxf(fmaxf(fmaxf(sc[0], sc[1]), fmaxf(sc[2], sc[3])), fmaxf(fmaxf(sc[4], sc[5]), fmaxf(sc[6], sc[7])));
;         mx = act ? mx : -1e30f;
;     ...
;     if (__builtin_amdgcn_ballot_w64(mx > st.m + 4.f) != 0ull) {
;         mx = fmaxf(mx, __shfl_xor(mx, 16)); mx = fmaxf(mx, __shfl_xor(mx, 32));
;         const float mn = fmaxf(st.m, mx), alpha = __builtin_amdgcn_exp2f(st.m - mn); st.m = mn; st.l *= alpha;
; #pragma unroll
;         for (int j = 0; j < 8; ++j) st.o[j] = st.o[j] * alpha;
;     }
.LBB0_711:
	v_lshl_add_u64 v[244:245], v[198:199], 0, v[98:99]
	global_load_dwordx4 v[132:135], v[244:245], off
	global_load_dwordx4 v[136:139], v[244:245], off offset:1024
	global_load_dwordx4 v[140:143], v[244:245], off offset:2048
	global_load_dwordx4 v[144:147], v[244:245], off offset:3072
	v_lshl_add_u64 v[246:247], v[196:197], 0, v[98:99]
	global_load_dwordx4 v[86:89], v[246:247], off
	global_load_dwordx4 v[90:93], v[246:247], off offset:1024
	global_load_dwordx4 v[94:97], v[246:247], off offset:2048
	global_load_dwordx4 v[112:115], v[246:247], off offset:3072
	s_waitcnt vmcnt(20)
	v_mfma_f32_16x16x128_f8f6f4 v[34:37], v[148:155], v[74:81], 0
	v_mfma_f32_16x16x128_f8f6f4 v[38:41], v[156:163], v[74:81], 0
	v_mov_b32_e32 v209, v207
	v_mov_b32_e32 v210, v208
	s_nop 8
	v_max3_f32 v0, v34, v35, v36
	v_max3_f32 v43, v37, v38, v39
	v_max3_f32 v0, v0, v40, v41
	v_max_f32_e32 v0, v0, v43
	v_cmp_gt_f32_e32 vcc, v0, v211
	s_cbranch_vccz .LBB0_713
	v_and_b32_e32 v43, 64, v204
	v_xor_b32_e32 v42, 16, v204
	v_add_u32_e32 v43, 64, v43
	v_cmp_lt_i32_e32 vcc, v42, v43
	v_xor_b32_e32 v44, 32, v204
	s_nop 0
	v_cndmask_b32_e32 v42, v204, v42, vcc
	v_lshlrev_b32_e32 v42, 2, v42
	ds_bpermute_b32 v42, v42, v0
	v_max_f32_e32 v0, v0, v0
	v_cmp_lt_i32_e32 vcc, v44, v43
	s_waitcnt lgkmcnt(0)
	v_max_f32_e32 v42, v42, v42
	v_max_f32_e32 v0, v0, v42
	v_cndmask_b32_e32 v42, v204, v44, vcc
	v_lshlrev_b32_e32 v42, 2, v42
	ds_bpermute_b32 v42, v42, v0
	s_waitcnt lgkmcnt(0)
	v_max3_f32 v209, v207, v0, v42
	v_sub_f32_e32 v0, v207, v209
	v_exp_f32_e32 v0, v0
	s_nop 0
	v_mul_f32_e32 v210, v208, v0
	v_pk_mul_f32 v[4:5], v[4:5], v[0:1] op_sel_hi:[1,0]
	v_pk_mul_f32 v[2:3], v[2:3], v[0:1] op_sel_hi:[1,0]
	v_pk_mul_f32 v[8:9], v[8:9], v[0:1] op_sel_hi:[1,0]
	v_pk_mul_f32 v[6:7], v[6:7], v[0:1] op_sel_hi:[1,0]
	v_pk_mul_f32 v[12:13], v[12:13], v[0:1] op_sel_hi:[1,0]
	v_pk_mul_f32 v[10:11], v[10:11], v[0:1] op_sel_hi:[1,0]
	v_pk_mul_f32 v[16:17], v[16:17], v[0:1] op_sel_hi:[1,0]
	v_pk_mul_f32 v[14:15], v[14:15], v[0:1] op_sel_hi:[1,0]
	v_pk_mul_f32 v[20:21], v[20:21], v[0:1] op_sel_hi:[1,0]
	v_pk_mul_f32 v[18:19], v[18:19], v[0:1] op_sel_hi:[1,0]
	v_pk_mul_f32 v[24:25], v[24:25], v[0:1] op_sel_hi:[1,0]
	v_pk_mul_f32 v[22:23], v[22:23], v[0:1] op_sel_hi:[1,0]
	v_pk_mul_f32 v[32:33], v[32:33], v[0:1] op_sel_hi:[1,0]
	v_pk_mul_f32 v[30:31], v[30:31], v[0:1] op_sel_hi:[1,0]
	v_pk_mul_f32 v[28:29], v[28:29], v[0:1] op_sel_hi:[1,0]
	v_pk_mul_f32 v[26:27], v[26:27], v[0:1] op_sel_hi:[1,0]

; template <bool SLC, bool NOMASK> ...
;     ...
;     if (NOMASK) {
; #pragma unroll
;         for (int j = 0; j < 8; ++j) { sc[j] = sa[j >> 2][j & 3]; vd[j] = act; }
;         mx = fmaxf(fmaxf(fmaxf(sc[0], sc[1]), fmaxf(sc[2], sc[3])), fmaxf(fmaxf(sc[4], sc[5]), fmaxf(sc[6], sc[7])));
;         mx = act ? mx : -1e30f;
;     ...
;     if (__builtin_amdgcn_ballot_w64(mx > st.m + 4.f) != 0ull) {
;         mx = fmaxf(mx, __shfl_xor(mx, 16)); mx = fmaxf(mx, __shfl_xor(mx, 32));
;         const float mn = fmaxf(st.m, mx), alpha = __builtin_amdgcn_exp2f(st.m - mn); st.m = mn; st.l *= alpha;
; #pragma unroll
;         for (int j = 0; j < 8; ++j) st.o[j] = st.o[j] * alpha;
;     }
; __device__ __forceinline__ void dilated_unit(int unit, const bf16_t* proj, const bf16_t* kbf, bf16_t* nsaout, int lane) {
;     ...
;         auto desc = [&](int i) { return 32 * (first + i); };
;         attn_run_frag8<false>(q8, kb8 + hoff, vb8 + hoff, desc, last - first + 1, lo, hi, 0, st, lane);
.LBB0_717:
	s_add_i32 s66, s66, 4
	s_min_i32 s4, s66, s74
	s_add_i32 s6, s4, s73
	s_lshl_b32 s76, s6, 5
	s_and_b32 s4, s76, 0x3fffffe0
	s_lshr_b32 s26, s4, 4
	s_lshl_b64 s[4:5], s[26:27], 11
	s_and_b32 s26, s6, 0x1ffffff
	s_and_b32 s8, s42, 0x2000000
	s_lshl_b64 s[6:7], s[26:27], 12
	s_cmp_eq_u32 s8, 0
	v_lshl_add_u64 v[198:199], v[82:83], 0, s[4:5]
	v_lshl_add_u64 v[196:197], v[84:85], 0, s[6:7]
	s_mov_b64 s[4:5], -1
	v_add_f32_e32 v211, 4.0, v209
	s_cbranch_scc1 .LBB0_721
	v_lshl_add_u64 v[244:245], v[198:199], 0, v[98:99]
	global_load_dwordx4 v[148:151], v[244:245], off
	global_load_dwordx4 v[152:155], v[244:245], off offset:1024
	global_load_dwordx4 v[156:159], v[244:245], off offset:2048
	global_load_dwordx4 v[160:163], v[244:245], off offset:3072
	v_lshl_add_u64 v[246:247], v[196:197], 0, v[98:99]
	global_load_dwordx4 v[116:119], v[246:247], off
	global_load_dwordx4 v[120:123], v[246:247], off offset:1024
	global_load_dwordx4 v[124:127], v[246:247], off offset:2048
	global_load_dwordx4 v[128:131], v[246:247], off offset:3072
	s_waitcnt vmcnt(20)
	v_mfma_f32_16x16x128_f8f6f4 v[2:5], v[180:187], v[74:81], 0
	v_mfma_f32_16x16x128_f8f6f4 v[6:9], v[188:195], v[74:81], 0
	v_mov_b32_e32 v207, v209
	v_mov_b32_e32 v208, v210
	s_nop 8
	v_max3_f32 v0, v2, v3, v4
	v_max3_f32 v12, v5, v6, v7
	v_max3_f32 v0, v0, v8, v9
	v_max_f32_e32 v0, v0, v12
	v_cmp_gt_f32_e32 vcc, v0, v211
	s_cbranch_vccz .LBB0_720
	v_and_b32_e32 v11, 64, v204
	v_xor_b32_e32 v10, 16, v204
	v_add_u32_e32 v11, 64, v11
	v_cmp_lt_i32_e32 vcc, v10, v11
	v_xor_b32_e32 v12, 32, v204
	s_nop 0
	v_cndmask_b32_e32 v10, v204, v10, vcc
	v_lshlrev_b32_e32 v10, 2, v10
	ds_bpermute_b32 v10, v10, v0
	v_max_f32_e32 v0, v0, v0
	v_cmp_lt_i32_e32 vcc, v12, v11
	s_waitcnt lgkmcnt(0)
	v_max_f32_e32 v10, v10, v10
	v_max_f32_e32 v0, v0, v10
	v_cndmask_b32_e32 v10, v204, v12, vcc
	v_lshlrev_b32_e32 v10, 2, v10
	ds_bpermute_b32 v10, v10, v0
	s_waitcnt lgkmcnt(0)
	v_max3_f32 v207, v209, v0, v10
	v_sub_f32_e32 v0, v209, v207
	v_exp_f32_e32 v0, v0
	s_nop 0
	v_mul_f32_e32 v208, v210, v0
	v_pk_mul_f32 v[36:37], v[36:37], v[0:1] op_sel_hi:[1,0]
	v_pk_mul_f32 v[34:35], v[34:35], v[0:1] op_sel_hi:[1,0]
	v_pk_mul_f32 v[40:41], v[40:41], v[0:1] op_sel_hi:[1,0]
	v_pk_mul_f32 v[38:39], v[38:39], v[0:1] op_sel_hi:[1,0]
	v_pk_mul_f32 v[44:45], v[44:45], v[0:1] op_sel_hi:[1,0]
	v_pk_mul_f32 v[42:43], v[42:43], v[0:1] op_sel_hi:[1,0]
	v_pk_mul_f32 v[48:49], v[48:49], v[0:1] op_sel_hi:[1,0]
	v_pk_mul_f32 v[46:47], v[46:47], v[0:1] op_sel_hi:[1,0]
	v_pk_mul_f32 v[52:53], v[52:53], v[0:1] op_sel_hi:[1,0]
	v_pk_mul_f32 v[50:51], v[50:51], v[0:1] op_sel_hi:[1,0]
	v_pk_mul_f32 v[56:57], v[56:57], v[0:1] op_sel_hi:[1,0]
	v_pk_mul_f32 v[54:55], v[54:55], v[0:1] op_sel_hi:[1,0]
	v_pk_mul_f32 v[60:61], v[60:61], v[0:1] op_sel_hi:[1,0]
	v_pk_mul_f32 v[58:59], v[58:59], v[0:1] op_sel_hi:[1,0]
	v_pk_mul_f32 v[64:65], v[64:65], v[0:1] op_sel_hi:[1,0]
	v_pk_mul_f32 v[62:63], v[62:63], v[0:1] op_sel_hi:[1,0]

; template <bool SLC, bool NOMASK> ...
;     ...
;     if (NOMASK) {
; #pragma unroll
;         for (int j = 0; j < 8; ++j) { sc[j] = sa[j >> 2][j & 3]; vd[j] = act; }
;         mx = fmaxf(fmaxf(fmaxf(sc[0], sc[1]), fmaxf(sc[2], sc[3])), fmaxf(fmaxf(sc[4], sc[5]), fmaxf(sc[6], sc[7])));
;         mx = act ? mx : -1e30f;
;     ...
;     if (__builtin_amdgcn_ballot_w64(mx > st.m + 4.f) != 0ull) {
;         mx = fmaxf(mx, __shfl_xor(mx, 16)); mx = fmaxf(mx, __shfl_xor(mx, 32));
;         const float mn = fmaxf(st.m, mx), alpha = __builtin_amdgcn_exp2f(st.m - mn); st.m = mn; st.l *= alpha;
; #pragma unroll
;         for (int j = 0; j < 8; ++j) st.o[j] = st.o[j] * alpha;
;     }
.LBB0_745:
	v_lshl_add_u64 v[244:245], v[198:199], 0, v[98:99]
	global_load_dwordx4 v[180:183], v[244:245], off
	global_load_dwordx4 v[184:187], v[244:245], off offset:1024
	global_load_dwordx4 v[188:191], v[244:245], off offset:2048
	global_load_dwordx4 v[192:195], v[244:245], off offset:3072
	v_lshl_add_u64 v[246:247], v[196:197], 0, v[98:99]
	global_load_dwordx4 v[164:167], v[246:247], off
	global_load_dwordx4 v[168:171], v[246:247], off offset:1024
	global_load_dwordx4 v[172:175], v[246:247], off offset:2048
	global_load_dwordx4 v[176:179], v[246:247], off offset:3072
	s_waitcnt vmcnt(20)
	v_mfma_f32_16x16x128_f8f6f4 v[2:5], v[132:139], v[74:81], 0
	v_mfma_f32_16x16x128_f8f6f4 v[6:9], v[140:147], v[74:81], 0
	v_mov_b32_e32 v205, v208
	v_mov_b32_e32 v206, v207
	s_nop 8
	v_max3_f32 v0, v2, v3, v4
	v_max3_f32 v12, v5, v6, v7
	v_max3_f32 v0, v0, v8, v9
	v_max_f32_e32 v0, v0, v12
	v_add_f32_e32 v10, 4.0, v208
	v_cmp_gt_f32_e32 vcc, v0, v10
	s_cbranch_vccz .LBB0_747
	v_and_b32_e32 v11, 64, v200
	v_xor_b32_e32 v10, 16, v200
	v_add_u32_e32 v11, 64, v11
	v_cmp_lt_i32_e32 vcc, v10, v11
	v_xor_b32_e32 v12, 32, v200
	s_nop 0
	v_cndmask_b32_e32 v10, v200, v10, vcc
	v_lshlrev_b32_e32 v10, 2, v10
	ds_bpermute_b32 v10, v10, v0
	v_max_f32_e32 v0, v0, v0
	v_cmp_lt_i32_e32 vcc, v12, v11
	s_waitcnt lgkmcnt(0)
	v_max_f32_e32 v10, v10, v10
	v_max_f32_e32 v0, v0, v10
	v_cndmask_b32_e32 v10, v200, v12, vcc
	v_lshlrev_b32_e32 v10, 2, v10
	ds_bpermute_b32 v10, v10, v0
	s_waitcnt lgkmcnt(0)
	v_max3_f32 v205, v208, v0, v10
	v_sub_f32_e32 v0, v208, v205
	v_exp_f32_e32 v0, v0
	s_nop 0
	v_mul_f32_e32 v206, v207, v0
	v_pk_mul_f32 v[36:37], v[36:37], v[0:1] op_sel_hi:[1,0]
	v_pk_mul_f32 v[34:35], v[34:35], v[0:1] op_sel_hi:[1,0]
	v_pk_mul_f32 v[40:41], v[40:41], v[0:1] op_sel_hi:[1,0]
	v_pk_mul_f32 v[38:39], v[38:39], v[0:1] op_sel_hi:[1,0]
	v_pk_mul_f32 v[44:45], v[44:45], v[0:1] op_sel_hi:[1,0]
	v_pk_mul_f32 v[42:43], v[42:43], v[0:1] op_sel_hi:[1,0]
	v_pk_mul_f32 v[56:57], v[56:57], v[0:1] op_sel_hi:[1,0]
	v_pk_mul_f32 v[54:55], v[54:55], v[0:1] op_sel_hi:[1,0]
	v_pk_mul_f32 v[64:65], v[64:65], v[0:1] op_sel_hi:[1,0]
	v_pk_mul_f32 v[62:63], v[62:63], v[0:1] op_sel_hi:[1,0]
	v_pk_mul_f32 v[60:61], v[60:61], v[0:1] op_sel_hi:[1,0]
	v_pk_mul_f32 v[58:59], v[58:59], v[0:1] op_sel_hi:[1,0]
	v_pk_mul_f32 v[52:53], v[52:53], v[0:1] op_sel_hi:[1,0]
	v_pk_mul_f32 v[50:51], v[50:51], v[0:1] op_sel_hi:[1,0]
	v_pk_mul_f32 v[48:49], v[48:49], v[0:1] op_sel_hi:[1,0]
	v_pk_mul_f32 v[46:47], v[46:47], v[0:1] op_sel_hi:[1,0]

; template <bool SLC, bool NOMASK> ...
;     ...
;     if (NOMASK) {
; #pragma unroll
;         for (int j = 0; j < 8; ++j) { sc[j] = sa[j >> 2][j & 3]; vd[j] = act; }
;         mx = fmaxf(fmaxf(fmaxf(sc[0], sc[1]), fmaxf(sc[2], sc[3])), fmaxf(fmaxf(sc[4], sc[5]), fmaxf(sc[6], sc[7])));
;         mx = act ? mx : -1e30f;
;     ...
;     if (__builtin_amdgcn_ballot_w64(mx > st.m + 4.f) != 0ull) {
;         mx = fmaxf(mx, __shfl_xor(mx, 16)); mx = fmaxf(mx, __shfl_xor(mx, 32));
;         const float mn = fmaxf(st.m, mx), alpha = __builtin_amdgcn_exp2f(st.m - mn); st.m = mn; st.l *= alpha;
; #pragma unroll
;         for (int j = 0; j < 8; ++j) st.o[j] = st.o[j] * alpha;
;     }
.LBB0_752:
	v_lshl_add_u64 v[244:245], v[198:199], 0, v[98:99]
	global_load_dwordx4 v[132:135], v[244:245], off
	global_load_dwordx4 v[136:139], v[244:245], off offset:1024
	global_load_dwordx4 v[140:143], v[244:245], off offset:2048
	global_load_dwordx4 v[144:147], v[244:245], off offset:3072
	v_lshl_add_u64 v[246:247], v[196:197], 0, v[98:99]
	global_load_dwordx4 v[86:89], v[246:247], off
	global_load_dwordx4 v[90:93], v[246:247], off offset:1024
	global_load_dwordx4 v[94:97], v[246:247], off offset:2048
	global_load_dwordx4 v[112:115], v[246:247], off offset:3072
	s_waitcnt vmcnt(20)
	v_mfma_f32_16x16x128_f8f6f4 v[34:37], v[148:155], v[74:81], 0
	v_mfma_f32_16x16x128_f8f6f4 v[38:41], v[156:163], v[74:81], 0
	v_mov_b32_e32 v207, v205
	v_mov_b32_e32 v208, v206
	s_nop 8
	v_max3_f32 v0, v34, v35, v36
	v_max3_f32 v43, v37, v38, v39
	v_max3_f32 v0, v0, v40, v41
	v_max_f32_e32 v0, v0, v43
	v_add_f32_e32 v42, 4.0, v205
	v_cmp_gt_f32_e32 vcc, v0, v42
	s_cbranch_vccz .LBB0_754
	v_and_b32_e32 v43, 64, v200
	v_xor_b32_e32 v42, 16, v200
	v_add_u32_e32 v43, 64, v43
	v_cmp_lt_i32_e32 vcc, v42, v43
	v_xor_b32_e32 v44, 32, v200
	s_nop 0
	v_cndmask_b32_e32 v42, v200, v42, vcc
	v_lshlrev_b32_e32 v42, 2, v42
	ds_bpermute_b32 v42, v42, v0
	v_max_f32_e32 v0, v0, v0
	v_cmp_lt_i32_e32 vcc, v44, v43
	s_waitcnt lgkmcnt(0)
	v_max_f32_e32 v42, v42, v42
	v_max_f32_e32 v0, v0, v42
	v_cndmask_b32_e32 v42, v200, v44, vcc
	v_lshlrev_b32_e32 v42, 2, v42
	ds_bpermute_b32 v42, v42, v0
	s_waitcnt lgkmcnt(0)
	v_max3_f32 v207, v205, v0, v42
	v_sub_f32_e32 v0, v205, v207
	v_exp_f32_e32 v0, v0
	s_nop 0
	v_mul_f32_e32 v208, v206, v0
	v_pk_mul_f32 v[4:5], v[4:5], v[0:1] op_sel_hi:[1,0]
	v_pk_mul_f32 v[2:3], v[2:3], v[0:1] op_sel_hi:[1,0]
	v_pk_mul_f32 v[8:9], v[8:9], v[0:1] op_sel_hi:[1,0]
	v_pk_mul_f32 v[6:7], v[6:7], v[0:1] op_sel_hi:[1,0]
	v_pk_mul_f32 v[12:13], v[12:13], v[0:1] op_sel_hi:[1,0]
	v_pk_mul_f32 v[10:11], v[10:11], v[0:1] op_sel_hi:[1,0]
	v_pk_mul_f32 v[16:17], v[16:17], v[0:1] op_sel_hi:[1,0]
	v_pk_mul_f32 v[14:15], v[14:15], v[0:1] op_sel_hi:[1,0]
	v_pk_mul_f32 v[20:21], v[20:21], v[0:1] op_sel_hi:[1,0]
	v_pk_mul_f32 v[18:19], v[18:19], v[0:1] op_sel_hi:[1,0]
	v_pk_mul_f32 v[24:25], v[24:25], v[0:1] op_sel_hi:[1,0]
	v_pk_mul_f32 v[22:23], v[22:23], v[0:1] op_sel_hi:[1,0]
	v_pk_mul_f32 v[32:33], v[32:33], v[0:1] op_sel_hi:[1,0]
	v_pk_mul_f32 v[30:31], v[30:31], v[0:1] op_sel_hi:[1,0]
	v_pk_mul_f32 v[28:29], v[28:29], v[0:1] op_sel_hi:[1,0]
	v_pk_mul_f32 v[26:27], v[26:27], v[0:1] op_sel_hi:[1,0]

; template <bool SLC, bool NOMASK> ...
;     ...
;     if (NOMASK) {
; #pragma unroll
;         for (int j = 0; j < 8; ++j) { sc[j] = sa[j >> 2][j & 3]; vd[j] = act; }
;         mx = fmaxf(fmaxf(fmaxf(sc[0], sc[1]), fmaxf(sc[2], sc[3])), fmaxf(fmaxf(sc[4], sc[5]), fmaxf(sc[6], sc[7])));
;         mx = act ? mx : -1e30f;
;     ...
;     if (__builtin_amdgcn_ballot_w64(mx > st.m + 4.f) != 0ull) {
;         mx = fmaxf(mx, __shfl_xor(mx, 16)); mx = fmaxf(mx, __shfl_xor(mx, 32));
;         const float mn = fmaxf(st.m, mx), alpha = __builtin_amdgcn_exp2f(st.m - mn); st.m = mn; st.l *= alpha;
; #pragma unroll
;         for (int j = 0; j < 8; ++j) st.o[j] = st.o[j] * alpha;
;     }
; __device__ __forceinline__ void dilated_unit(int unit, const bf16_t* proj, const bf16_t* kbf, bf16_t* nsaout, int lane) {
;     ...
;         auto desc = [&](int i) { return 32 * (first + i); };
;         attn_run_frag8<false>(q8, kb8 + hoff, vb8 + hoff, desc, last - first + 1, lo, hi, 0, st, lane);
.LBB0_758:
	s_add_i32 s66, s66, 4
	s_min_i32 s4, s66, s61
	s_add_i32 s6, s4, s60
	s_lshl_b32 s63, s6, 5
	s_and_b32 s4, s63, 0x3fffffe0
	s_lshr_b32 s24, s4, 4
	s_lshl_b64 s[4:5], s[24:25], 11
	s_and_b32 s24, s6, 0x1ffffff
	s_and_b32 s8, s42, 0x2000000
	s_lshl_b64 s[6:7], s[24:25], 12
	s_cmp_eq_u32 s8, 0
	v_lshl_add_u64 v[198:199], v[82:83], 0, s[4:5]
	v_lshl_add_u64 v[196:197], v[84:85], 0, s[6:7]
	s_mov_b64 s[4:5], -1
	v_add_f32_e32 v209, 4.0, v207
	s_cbranch_scc1 .LBB0_762
	v_lshl_add_u64 v[244:245], v[198:199], 0, v[98:99]
	global_load_dwordx4 v[148:151], v[244:245], off
	global_load_dwordx4 v[152:155], v[244:245], off offset:1024
	global_load_dwordx4 v[156:159], v[244:245], off offset:2048
	global_load_dwordx4 v[160:163], v[244:245], off offset:3072
	v_lshl_add_u64 v[246:247], v[196:197], 0, v[98:99]
	global_load_dwordx4 v[116:119], v[246:247], off
	global_load_dwordx4 v[120:123], v[246:247], off offset:1024
	global_load_dwordx4 v[124:127], v[246:247], off offset:2048
	global_load_dwordx4 v[128:131], v[246:247], off offset:3072
	s_waitcnt vmcnt(20)
	v_mfma_f32_16x16x128_f8f6f4 v[2:5], v[180:187], v[74:81], 0
	v_mfma_f32_16x16x128_f8f6f4 v[6:9], v[188:195], v[74:81], 0
	v_mov_b32_e32 v205, v207
	v_mov_b32_e32 v206, v208
	s_nop 8
	v_max3_f32 v0, v2, v3, v4
	v_max3_f32 v12, v5, v6, v7
	v_max3_f32 v0, v0, v8, v9
	v_max_f32_e32 v0, v0, v12
	v_cmp_gt_f32_e32 vcc, v0, v209
	s_cbranch_vccz .LBB0_761
	v_and_b32_e32 v11, 64, v200
	v_xor_b32_e32 v10, 16, v200
	v_add_u32_e32 v11, 64, v11
	v_cmp_lt_i32_e32 vcc, v10, v11
	v_xor_b32_e32 v12, 32, v200
	s_nop 0
	v_cndmask_b32_e32 v10, v200, v10, vcc
	v_lshlrev_b32_e32 v10, 2, v10
	ds_bpermute_b32 v10, v10, v0
	v_max_f32_e32 v0, v0, v0
	v_cmp_lt_i32_e32 vcc, v12, v11
	s_waitcnt lgkmcnt(0)
	v_max_f32_e32 v10, v10, v10
	v_max_f32_e32 v0, v0, v10
	v_cndmask_b32_e32 v10, v200, v12, vcc
	v_lshlrev_b32_e32 v10, 2, v10
	ds_bpermute_b32 v10, v10, v0
	s_waitcnt lgkmcnt(0)
	v_max3_f32 v205, v207, v0, v10
	v_sub_f32_e32 v0, v207, v205
	v_exp_f32_e32 v0, v0
	s_nop 0
	v_mul_f32_e32 v206, v208, v0
	v_pk_mul_f32 v[36:37], v[36:37], v[0:1] op_sel_hi:[1,0]
	v_pk_mul_f32 v[34:35], v[34:35], v[0:1] op_sel_hi:[1,0]
	v_pk_mul_f32 v[40:41], v[40:41], v[0:1] op_sel_hi:[1,0]
	v_pk_mul_f32 v[38:39], v[38:39], v[0:1] op_sel_hi:[1,0]
	v_pk_mul_f32 v[44:45], v[44:45], v[0:1] op_sel_hi:[1,0]
	v_pk_mul_f32 v[42:43], v[42:43], v[0:1] op_sel_hi:[1,0]
	v_pk_mul_f32 v[48:49], v[48:49], v[0:1] op_sel_hi:[1,0]
	v_pk_mul_f32 v[46:47], v[46:47], v[0:1] op_sel_hi:[1,0]
	v_pk_mul_f32 v[52:53], v[52:53], v[0:1] op_sel_hi:[1,0]
	v_pk_mul_f32 v[50:51], v[50:51], v[0:1] op_sel_hi:[1,0]
	v_pk_mul_f32 v[56:57], v[56:57], v[0:1] op_sel_hi:[1,0]
	v_pk_mul_f32 v[54:55], v[54:55], v[0:1] op_sel_hi:[1,0]
	v_pk_mul_f32 v[60:61], v[60:61], v[0:1] op_sel_hi:[1,0]
	v_pk_mul_f32 v[58:59], v[58:59], v[0:1] op_sel_hi:[1,0]
	v_pk_mul_f32 v[64:65], v[64:65], v[0:1] op_sel_hi:[1,0]
	v_pk_mul_f32 v[62:63], v[62:63], v[0:1] op_sel_hi:[1,0]

; template <bool SLC, bool NOMASK> ...
;     ...
;     if (NOMASK) {
; #pragma unroll
;         for (int j = 0; j < 8; ++j) { sc[j] = sa[j >> 2][j & 3]; vd[j] = act; }
;         mx = fmaxf(fmaxf(fmaxf(sc[0], sc[1]), fmaxf(sc[2], sc[3])), fmaxf(fmaxf(sc[4], sc[5]), fmaxf(sc[6], sc[7])));
;         mx = act ? mx : -1e30f;
;     ...
;     if (__builtin_amdgcn_ballot_w64(mx > st.m + 4.f) != 0ull) {
;         mx = fmaxf(mx, __shfl_xor(mx, 16)); mx = fmaxf(mx, __shfl_xor(mx, 32));
;         const float mn = fmaxf(st.m, mx), alpha = __builtin_amdgcn_exp2f(st.m - mn); st.m = mn; st.l *= alpha;
; #pragma unroll
;         for (int j = 0; j < 8; ++j) st.o[j] = st.o[j] * alpha;
;     }
.LBB0_867:
	s_and_b32 s13, s12, 0xfffffbff
	s_cmp_eq_u32 s13, 4
	s_cselect_b64 s[10:11], -1, 0
	s_lshl_b32 s14, s66, 7
	s_and_b32 s50, s14, 0x7fff800
	v_lshl_add_u64 v[10:11], v[86:87], 0, s[50:51]
	s_and_b32 s50, s14, 0x7fff000
	v_lshl_add_u64 v[244:245], v[10:11], 0, v[118:119]
	global_load_dwordx4 v[186:189], v[244:245], off
	global_load_dwordx4 v[190:193], v[244:245], off offset:1024
	global_load_dwordx4 v[194:197], v[244:245], off offset:2048
	global_load_dwordx4 v[198:201], v[244:245], off offset:3072
	v_lshl_add_u64 v[10:11], v[88:89], 0, s[50:51]
	v_lshl_add_u64 v[246:247], v[10:11], 0, v[118:119]
	global_load_dwordx4 v[170:173], v[246:247], off
	global_load_dwordx4 v[174:177], v[246:247], off offset:1024
	global_load_dwordx4 v[178:181], v[246:247], off offset:2048
	global_load_dwordx4 v[182:185], v[246:247], off offset:3072
	s_waitcnt vmcnt(20)
	v_mfma_f32_16x16x128_f8f6f4 v[2:5], v[138:145], v[78:85], 0
	v_cmp_eq_u32_e32 vcc, s13, v209
	s_or_b64 s[10:11], s[10:11], vcc
	v_mfma_f32_16x16x128_f8f6f4 v[6:9], v[146:153], v[78:85], 0
	v_mov_b32_e32 v133, v203
	s_nop 9
	v_max3_f32 v0, v2, v3, v4
	v_max3_f32 v12, v5, v6, v7
	v_max3_f32 v0, v0, v8, v9
	v_max_f32_e32 v0, v0, v12
	v_cndmask_b32_e64 v34, v223, v0, s[10:11]
	v_cmp_gt_f32_e32 vcc, v34, v204
	v_mov_b32_e32 v0, v202
	s_cbranch_vccz .LBB0_869
	ds_bpermute_b32 v0, v227, v34
	v_max_f32_e32 v10, v34, v34
	s_waitcnt lgkmcnt(0)
	v_max_f32_e32 v0, v0, v0
	v_max_f32_e32 v0, v10, v0
	ds_bpermute_b32 v10, v226, v0
	s_waitcnt lgkmcnt(0)
	v_max3_f32 v0, v202, v0, v10
	v_sub_f32_e32 v10, v202, v0
	v_exp_f32_e32 v34, v10
	s_nop 0
	v_mul_f32_e32 v133, v203, v34
	v_pk_mul_f32 v[66:67], v[66:67], v[34:35] op_sel_hi:[1,0]
	v_pk_mul_f32 v[64:65], v[64:65], v[34:35] op_sel_hi:[1,0]
	v_pk_mul_f32 v[62:63], v[62:63], v[34:35] op_sel_hi:[1,0]
	v_pk_mul_f32 v[60:61], v[60:61], v[34:35] op_sel_hi:[1,0]
	v_pk_mul_f32 v[58:59], v[58:59], v[34:35] op_sel_hi:[1,0]
	v_pk_mul_f32 v[56:57], v[56:57], v[34:35] op_sel_hi:[1,0]
	v_pk_mul_f32 v[54:55], v[54:55], v[34:35] op_sel_hi:[1,0]
	v_pk_mul_f32 v[52:53], v[52:53], v[34:35] op_sel_hi:[1,0]
	v_pk_mul_f32 v[50:51], v[50:51], v[34:35] op_sel_hi:[1,0]
	v_pk_mul_f32 v[48:49], v[48:49], v[34:35] op_sel_hi:[1,0]
	v_pk_mul_f32 v[46:47], v[46:47], v[34:35] op_sel_hi:[1,0]
	v_pk_mul_f32 v[44:45], v[44:45], v[34:35] op_sel_hi:[1,0]
	v_pk_mul_f32 v[42:43], v[42:43], v[34:35] op_sel_hi:[1,0]
	v_pk_mul_f32 v[40:41], v[40:41], v[34:35] op_sel_hi:[1,0]
	v_pk_mul_f32 v[38:39], v[38:39], v[34:35] op_sel_hi:[1,0]
	v_pk_mul_f32 v[36:37], v[36:37], v[34:35] op_sel_hi:[1,0]

; template <bool SLC, bool NOMASK> ...
;     ...
;     if (NOMASK) {
; #pragma unroll
;         for (int j = 0; j < 8; ++j) { sc[j] = sa[j >> 2][j & 3]; vd[j] = act; }
;         mx = fmaxf(fmaxf(fmaxf(sc[0], sc[1]), fmaxf(sc[2], sc[3])), fmaxf(fmaxf(sc[4], sc[5]), fmaxf(sc[6], sc[7])));
;         mx = act ? mx : -1e30f;
;     ...
;     if (__builtin_amdgcn_ballot_w64(mx > st.m + 4.f) != 0ull) {
;         mx = fmaxf(mx, __shfl_xor(mx, 16)); mx = fmaxf(mx, __shfl_xor(mx, 32));
;         const float mn = fmaxf(st.m, mx), alpha = __builtin_amdgcn_exp2f(st.m - mn); st.m = mn; st.l *= alpha;
; #pragma unroll
;         for (int j = 0; j < 8; ++j) st.o[j] = st.o[j] * alpha;
;     }
.LBB0_874:
	s_and_b32 s13, s12, 0xfffffbff
	s_cmp_eq_u32 s13, 4
	s_cselect_b64 s[10:11], -1, 0
	s_lshl_b32 s14, s59, 7
	s_and_b32 s50, s14, 0x7fff800
	v_lshl_add_u64 v[44:45], v[86:87], 0, s[50:51]
	s_and_b32 s50, s14, 0x7fff000
	v_lshl_add_u64 v[244:245], v[44:45], 0, v[118:119]
	global_load_dwordx4 v[138:141], v[244:245], off
	global_load_dwordx4 v[142:145], v[244:245], off offset:1024
	global_load_dwordx4 v[146:149], v[244:245], off offset:2048
	global_load_dwordx4 v[150:153], v[244:245], off offset:3072
	v_lshl_add_u64 v[44:45], v[88:89], 0, s[50:51]
	v_lshl_add_u64 v[246:247], v[44:45], 0, v[118:119]
	global_load_dwordx4 v[90:93], v[246:247], off
	global_load_dwordx4 v[94:97], v[246:247], off offset:1024
	global_load_dwordx4 v[98:101], v[246:247], off offset:2048
	global_load_dwordx4 v[102:105], v[246:247], off offset:3072
	s_waitcnt vmcnt(20)
	v_mfma_f32_16x16x128_f8f6f4 v[36:39], v[154:161], v[78:85], 0
	v_cmp_eq_u32_e32 vcc, s13, v209
	s_or_b64 s[10:11], s[10:11], vcc
	v_mfma_f32_16x16x128_f8f6f4 v[40:43], v[162:169], v[78:85], 0
	v_mov_b32_e32 v203, v0
	s_nop 9
	v_max3_f32 v3, v36, v37, v38
	v_max3_f32 v45, v39, v40, v41
	v_max3_f32 v3, v3, v42, v43
	v_max_f32_e32 v3, v3, v45
	v_cndmask_b32_e64 v202, v223, v3, s[10:11]
	v_cmp_gt_f32_e32 vcc, v202, v2
	v_mov_b32_e32 v3, v133
	s_cbranch_vccz .LBB0_876
	ds_bpermute_b32 v3, v227, v202
	v_max_f32_e32 v44, v202, v202
	s_waitcnt lgkmcnt(0)
	v_max_f32_e32 v3, v3, v3
	v_max_f32_e32 v3, v44, v3
	ds_bpermute_b32 v44, v226, v3
	s_waitcnt lgkmcnt(0)
	v_max3_f32 v203, v0, v3, v44
	v_sub_f32_e32 v3, v0, v203
	v_exp_f32_e32 v72, v3
	s_nop 0
	v_mul_f32_e32 v3, v133, v72
	v_pk_mul_f32 v[10:11], v[10:11], v[72:73] op_sel_hi:[1,0]
	v_pk_mul_f32 v[8:9], v[8:9], v[72:73] op_sel_hi:[1,0]
	v_pk_mul_f32 v[14:15], v[14:15], v[72:73] op_sel_hi:[1,0]
	v_pk_mul_f32 v[12:13], v[12:13], v[72:73] op_sel_hi:[1,0]
	v_pk_mul_f32 v[18:19], v[18:19], v[72:73] op_sel_hi:[1,0]
	v_pk_mul_f32 v[16:17], v[16:17], v[72:73] op_sel_hi:[1,0]
	v_pk_mul_f32 v[22:23], v[22:23], v[72:73] op_sel_hi:[1,0]
	v_pk_mul_f32 v[20:21], v[20:21], v[72:73] op_sel_hi:[1,0]
	v_pk_mul_f32 v[26:27], v[26:27], v[72:73] op_sel_hi:[1,0]
	v_pk_mul_f32 v[24:25], v[24:25], v[72:73] op_sel_hi:[1,0]
	v_pk_mul_f32 v[34:35], v[34:35], v[72:73] op_sel_hi:[1,0]
	v_pk_mul_f32 v[32:33], v[32:33], v[72:73] op_sel_hi:[1,0]
	v_pk_mul_f32 v[30:31], v[30:31], v[72:73] op_sel_hi:[1,0]
	v_pk_mul_f32 v[28:29], v[28:29], v[72:73] op_sel_hi:[1,0]
	v_pk_mul_f32 v[6:7], v[6:7], v[72:73] op_sel_hi:[1,0]
	v_pk_mul_f32 v[4:5], v[4:5], v[72:73] op_sel_hi:[1,0]

; #define F8_STEP(CUR, NXT2, DC, DN2) do { \
;         if ((DC) & (1 << 30)) step_frag8<SLC, true>(qf, CUR, NXT2, KF, VF, (DC) & NM, (DN2) & NM, lo_in, hi, qi, st, lane); \
;         else step_frag8<SLC, false>(qf, CUR, NXT2, KF, VF, (DC), (DN2) & NM, lo_in, hi, qi, st, lane); } while (0)
; template <bool SLC, bool NOMASK> ...
;     ...
;     if (NOMASK) {
; #pragma unroll
;         for (int j = 0; j < 8; ++j) { sc[j] = sa[j >> 2][j & 3]; vd[j] = act; }
;         mx = fmaxf(fmaxf(fmaxf(sc[0], sc[1]), fmaxf(sc[2], sc[3])), fmaxf(fmaxf(sc[4], sc[5]), fmaxf(sc[6], sc[7])));
;         mx = act ? mx : -1e30f;
;     ...
;     if (__builtin_amdgcn_ballot_w64(mx > st.m + 4.f) != 0ull) {
;         mx = fmaxf(mx, __shfl_xor(mx, 16)); mx = fmaxf(mx, __shfl_xor(mx, 32));
;         const float mn = fmaxf(st.m, mx), alpha = __builtin_amdgcn_exp2f(st.m - mn); st.m = mn; st.l *= alpha;
; #pragma unroll
;         for (int j = 0; j < 8; ++j) st.o[j] = st.o[j] * alpha;
;     }
; template <bool SLC, class Desc>
; __device__ __forceinline__ void attn_run_frag8(const i64_t (&qf)[4], const unsigned char* __restrict__ KF, const unsigned char* __restrict__ VF, const Desc& desc, int n,
;                                                int lo_in, int hi, int qi, AState& st, int lane) {
;     ...
;     for (int i = 0; i < n; i += 3) {
;         const int d2 = desc(i + 2 < n ? i + 2 : n - 1);
;         F8_STEP(fa, fc, d0, d2);
;         if (i + 1 >= n) break;
;         const int d3 = desc(i + 3 < n ? i + 3 : n - 1);
;         F8_STEP(fb, fa, d1, d3);
;         if (i + 2 >= n) break;
;         const int d4 = desc(i + 4 < n ? i + 4 : n - 1);
;         F8_STEP(fc, fb, d2, d4);
.LBB0_880:
	s_cmp_lt_u32 s58, s56
	s_cselect_b32 s10, s58, s57
	s_lshl_b32 s10, s10, 2
	s_add_i32 s10, s3, s10
	v_mov_b32_e32 v0, s10
	ds_read_b32 v0, v0 offset:13632
	s_and_b32 s13, s66, 2.0
	s_ashr_i32 s12, s66, 20
	s_mov_b64 s[10:11], -1
	s_cmp_eq_u32 s13, 0
	s_waitcnt lgkmcnt(0)
	v_readfirstlane_b32 s97, v0
	v_add_f32_e32 v0, 4.0, v203
	s_cbranch_scc1 .LBB0_884
	s_and_b32 s13, s12, 0xfffffbff
	s_cmp_eq_u32 s13, 4
	s_cselect_b64 s[10:11], -1, 0
	s_lshl_b32 s14, s97, 7
	s_and_b32 s50, s14, 0x7fff800
	v_lshl_add_u64 v[10:11], v[86:87], 0, s[50:51]
	s_and_b32 s50, s14, 0x7fff000
	v_lshl_add_u64 v[244:245], v[10:11], 0, v[118:119]
	global_load_dwordx4 v[154:157], v[244:245], off
	global_load_dwordx4 v[158:161], v[244:245], off offset:1024
	global_load_dwordx4 v[162:165], v[244:245], off offset:2048
	global_load_dwordx4 v[166:169], v[244:245], off offset:3072
	v_lshl_add_u64 v[10:11], v[88:89], 0, s[50:51]
	v_lshl_add_u64 v[246:247], v[10:11], 0, v[118:119]
	global_load_dwordx4 v[106:109], v[246:247], off
	global_load_dwordx4 v[110:113], v[246:247], off offset:1024
	global_load_dwordx4 v[114:117], v[246:247], off offset:2048
	global_load_dwordx4 v[134:137], v[246:247], off offset:3072
	s_waitcnt vmcnt(20)
	v_mfma_f32_16x16x128_f8f6f4 v[2:5], v[186:193], v[78:85], 0
	v_cmp_eq_u32_e32 vcc, s13, v209
	s_or_b64 s[10:11], s[10:11], vcc
	v_mfma_f32_16x16x128_f8f6f4 v[6:9], v[194:201], v[78:85], 0
	v_mov_b32_e32 v202, v203
	v_mov_b32_e32 v133, v204
	s_nop 8
	v_max3_f32 v10, v2, v3, v4
	v_max3_f32 v12, v5, v6, v7
	v_max3_f32 v10, v10, v8, v9
	v_max_f32_e32 v10, v10, v12
	v_cndmask_b32_e64 v34, v223, v10, s[10:11]
	v_cmp_gt_f32_e32 vcc, v34, v0
	s_cbranch_vccz .LBB0_883
	ds_bpermute_b32 v10, v227, v34
	v_max_f32_e32 v11, v34, v34
	s_waitcnt lgkmcnt(0)
	v_max_f32_e32 v10, v10, v10
	v_max_f32_e32 v10, v11, v10
	ds_bpermute_b32 v11, v226, v10
	s_waitcnt lgkmcnt(0)
	v_max3_f32 v202, v203, v10, v11
	v_sub_f32_e32 v10, v203, v202
	v_exp_f32_e32 v34, v10
	s_nop 0
	v_mul_f32_e32 v133, v204, v34
	v_pk_mul_f32 v[38:39], v[38:39], v[34:35] op_sel_hi:[1,0]
	v_pk_mul_f32 v[36:37], v[36:37], v[34:35] op_sel_hi:[1,0]
	v_pk_mul_f32 v[42:43], v[42:43], v[34:35] op_sel_hi:[1,0]
	v_pk_mul_f32 v[40:41], v[40:41], v[34:35] op_sel_hi:[1,0]
	v_pk_mul_f32 v[46:47], v[46:47], v[34:35] op_sel_hi:[1,0]
	v_pk_mul_f32 v[44:45], v[44:45], v[34:35] op_sel_hi:[1,0]
	v_pk_mul_f32 v[50:51], v[50:51], v[34:35] op_sel_hi:[1,0]
	v_pk_mul_f32 v[48:49], v[48:49], v[34:35] op_sel_hi:[1,0]
	v_pk_mul_f32 v[54:55], v[54:55], v[34:35] op_sel_hi:[1,0]
	v_pk_mul_f32 v[52:53], v[52:53], v[34:35] op_sel_hi:[1,0]
	v_pk_mul_f32 v[58:59], v[58:59], v[34:35] op_sel_hi:[1,0]
	v_pk_mul_f32 v[56:57], v[56:57], v[34:35] op_sel_hi:[1,0]
	v_pk_mul_f32 v[62:63], v[62:63], v[34:35] op_sel_hi:[1,0]
	v_pk_mul_f32 v[60:61], v[60:61], v[34:35] op_sel_hi:[1,0]
	v_pk_mul_f32 v[66:67], v[66:67], v[34:35] op_sel_hi:[1,0]
	v_pk_mul_f32 v[64:65], v[64:65], v[34:35] op_sel_hi:[1,0]

; template <bool SLC, bool NOMASK> ...
;     ...
;     if (NOMASK) {
; #pragma unroll
;         for (int j = 0; j < 8; ++j) { sc[j] = sa[j >> 2][j & 3]; vd[j] = act; }
;         mx = fmaxf(fmaxf(fmaxf(sc[0], sc[1]), fmaxf(sc[2], sc[3])), fmaxf(fmaxf(sc[4], sc[5]), fmaxf(sc[6], sc[7])));
;         mx = act ? mx : -1e30f;
;     ...
;     if (__builtin_amdgcn_ballot_w64(mx > st.m + 4.f) != 0ull) {
;         mx = fmaxf(mx, __shfl_xor(mx, 16)); mx = fmaxf(mx, __shfl_xor(mx, 32));
;         const float mn = fmaxf(st.m, mx), alpha = __builtin_amdgcn_exp2f(st.m - mn); st.m = mn; st.l *= alpha;
; #pragma unroll
;         for (int j = 0; j < 8; ++j) st.o[j] = st.o[j] * alpha;
;     }
.LBB0_900:
	v_lshl_add_u64 v[244:245], v[204:205], 0, v[118:119]
	global_load_dwordx4 v[186:189], v[244:245], off
	global_load_dwordx4 v[190:193], v[244:245], off offset:1024
	global_load_dwordx4 v[194:197], v[244:245], off offset:2048
	global_load_dwordx4 v[198:201], v[244:245], off offset:3072
	v_lshl_add_u64 v[246:247], v[202:203], 0, v[118:119]
	global_load_dwordx4 v[170:173], v[246:247], off
	global_load_dwordx4 v[174:177], v[246:247], off offset:1024
	global_load_dwordx4 v[178:181], v[246:247], off offset:2048
	global_load_dwordx4 v[182:185], v[246:247], off offset:3072
	s_waitcnt vmcnt(20)
	v_mfma_f32_16x16x128_f8f6f4 v[2:5], v[138:145], v[78:85], 0
	v_mfma_f32_16x16x128_f8f6f4 v[6:9], v[146:153], v[78:85], 0
	v_mov_b32_e32 v229, v133
	v_mov_b32_e32 v34, v230
	s_nop 8
	v_max3_f32 v0, v2, v3, v4
	v_max3_f32 v12, v5, v6, v7
	v_max3_f32 v0, v0, v8, v9
	v_max_f32_e32 v0, v0, v12
	v_cmp_gt_f32_e32 vcc, v0, v231
	s_cbranch_vccz .LBB0_902
	ds_bpermute_b32 v10, v227, v0
	v_max_f32_e32 v0, v0, v0
	s_waitcnt lgkmcnt(0)
	v_max_f32_e32 v10, v10, v10
	v_max_f32_e32 v0, v0, v10
	ds_bpermute_b32 v10, v226, v0
	s_waitcnt lgkmcnt(0)
	v_max3_f32 v229, v133, v0, v10
	v_sub_f32_e32 v0, v133, v229
	v_exp_f32_e32 v0, v0
	s_nop 0
	v_mul_f32_e32 v34, v230, v0
	v_pk_mul_f32 v[66:67], v[66:67], v[0:1] op_sel_hi:[1,0]
	v_pk_mul_f32 v[64:65], v[64:65], v[0:1] op_sel_hi:[1,0]
	v_pk_mul_f32 v[62:63], v[62:63], v[0:1] op_sel_hi:[1,0]
	v_pk_mul_f32 v[60:61], v[60:61], v[0:1] op_sel_hi:[1,0]
	v_pk_mul_f32 v[58:59], v[58:59], v[0:1] op_sel_hi:[1,0]
	v_pk_mul_f32 v[56:57], v[56:57], v[0:1] op_sel_hi:[1,0]
	v_pk_mul_f32 v[54:55], v[54:55], v[0:1] op_sel_hi:[1,0]
	v_pk_mul_f32 v[52:53], v[52:53], v[0:1] op_sel_hi:[1,0]
	v_pk_mul_f32 v[50:51], v[50:51], v[0:1] op_sel_hi:[1,0]
	v_pk_mul_f32 v[48:49], v[48:49], v[0:1] op_sel_hi:[1,0]
	v_pk_mul_f32 v[46:47], v[46:47], v[0:1] op_sel_hi:[1,0]
	v_pk_mul_f32 v[44:45], v[44:45], v[0:1] op_sel_hi:[1,0]
	v_pk_mul_f32 v[42:43], v[42:43], v[0:1] op_sel_hi:[1,0]
	v_pk_mul_f32 v[40:41], v[40:41], v[0:1] op_sel_hi:[1,0]
	v_pk_mul_f32 v[38:39], v[38:39], v[0:1] op_sel_hi:[1,0]
	v_pk_mul_f32 v[36:37], v[36:37], v[0:1] op_sel_hi:[1,0]

; template <bool SLC, bool NOMASK> ...
;     ...
;     if (NOMASK) {
; #pragma unroll
;         for (int j = 0; j < 8; ++j) { sc[j] = sa[j >> 2][j & 3]; vd[j] = act; }
;         mx = fmaxf(fmaxf(fmaxf(sc[0], sc[1]), fmaxf(sc[2], sc[3])), fmaxf(fmaxf(sc[4], sc[5]), fmaxf(sc[6], sc[7])));
;         mx = act ? mx : -1e30f;
;     ...
;     if (__builtin_amdgcn_ballot_w64(mx > st.m + 4.f) != 0ull) {
;         mx = fmaxf(mx, __shfl_xor(mx, 16)); mx = fmaxf(mx, __shfl_xor(mx, 32));
;         const float mn = fmaxf(st.m, mx), alpha = __builtin_amdgcn_exp2f(st.m - mn); st.m = mn; st.l *= alpha;
; #pragma unroll
;         for (int j = 0; j < 8; ++j) st.o[j] = st.o[j] * alpha;
;     }
.LBB0_907:
	v_lshl_add_u64 v[244:245], v[204:205], 0, v[118:119]
	global_load_dwordx4 v[138:141], v[244:245], off
	global_load_dwordx4 v[142:145], v[244:245], off offset:1024
	global_load_dwordx4 v[146:149], v[244:245], off offset:2048
	global_load_dwordx4 v[150:153], v[244:245], off offset:3072
	v_lshl_add_u64 v[246:247], v[202:203], 0, v[118:119]
	global_load_dwordx4 v[90:93], v[246:247], off
	global_load_dwordx4 v[94:97], v[246:247], off offset:1024
	global_load_dwordx4 v[98:101], v[246:247], off offset:2048
	global_load_dwordx4 v[102:105], v[246:247], off offset:3072
	s_waitcnt vmcnt(20)
	v_mfma_f32_16x16x128_f8f6f4 v[36:39], v[154:161], v[78:85], 0
	v_mfma_f32_16x16x128_f8f6f4 v[40:43], v[162:169], v[78:85], 0
	v_mov_b32_e32 v230, v229
	v_mov_b32_e32 v231, v34
	s_nop 8
	v_max3_f32 v0, v36, v37, v38
	v_max3_f32 v45, v39, v40, v41
	v_max3_f32 v0, v0, v42, v43
	v_max_f32_e32 v0, v0, v45
	v_cmp_gt_f32_e32 vcc, v0, v133
	s_cbranch_vccz .LBB0_909
	ds_bpermute_b32 v44, v227, v0
	v_max_f32_e32 v0, v0, v0
	s_waitcnt lgkmcnt(0)
	v_max_f32_e32 v44, v44, v44
	v_max_f32_e32 v0, v0, v44
	ds_bpermute_b32 v44, v226, v0
	s_waitcnt lgkmcnt(0)
	v_max3_f32 v230, v229, v0, v44
	v_sub_f32_e32 v0, v229, v230
	v_exp_f32_e32 v0, v0
	s_nop 0
	v_mul_f32_e32 v231, v34, v0
	v_pk_mul_f32 v[8:9], v[8:9], v[0:1] op_sel_hi:[1,0]
	v_pk_mul_f32 v[6:7], v[6:7], v[0:1] op_sel_hi:[1,0]
	v_pk_mul_f32 v[12:13], v[12:13], v[0:1] op_sel_hi:[1,0]
	v_pk_mul_f32 v[10:11], v[10:11], v[0:1] op_sel_hi:[1,0]
	v_pk_mul_f32 v[16:17], v[16:17], v[0:1] op_sel_hi:[1,0]
	v_pk_mul_f32 v[14:15], v[14:15], v[0:1] op_sel_hi:[1,0]
	v_pk_mul_f32 v[20:21], v[20:21], v[0:1] op_sel_hi:[1,0]
	v_pk_mul_f32 v[18:19], v[18:19], v[0:1] op_sel_hi:[1,0]
	v_pk_mul_f32 v[24:25], v[24:25], v[0:1] op_sel_hi:[1,0]
	v_pk_mul_f32 v[22:23], v[22:23], v[0:1] op_sel_hi:[1,0]
	v_pk_mul_f32 v[28:29], v[28:29], v[0:1] op_sel_hi:[1,0]
	v_pk_mul_f32 v[26:27], v[26:27], v[0:1] op_sel_hi:[1,0]
	v_pk_mul_f32 v[32:33], v[32:33], v[0:1] op_sel_hi:[1,0]
	v_pk_mul_f32 v[30:31], v[30:31], v[0:1] op_sel_hi:[1,0]
	v_pk_mul_f32 v[4:5], v[4:5], v[0:1] op_sel_hi:[1,0]
	v_pk_mul_f32 v[2:3], v[2:3], v[0:1] op_sel_hi:[1,0]

; template <bool SLC, bool NOMASK> ...
;     const int kq = lane >> 4;
;     const int pos0 = SLC ? (dcur & 0xfffff) : dcur;
;     const int lo = SLC ? ((((dcur >> 20) == qi) | ((dcur >> 20) == 4)) ? 0 : (1 << 30)) : lo_in;
;     load_frag8(nxt, KF, VF, SLC ? (dnext & 0xfffff) : dnext, lane);
;     f32x4 sa[2] = {(f32x4){0.f, 0.f, 0.f, 0.f}, (f32x4){0.f, 0.f, 0.f, 0.f}};
; #pragma unroll
;     for (int T = 0; T < 2; ++T)
; #pragma unroll
;         for (int s2 = 0; s2 < 4; ++s2) sa[T] = __builtin_amdgcn_mfma_f32_16x16x32_fp8_fp8(cur.k[T][s2], qf[s2], sa[T], 0, 0, 0);
;     float sc[8]; bool vd[8]; float mx = -1e30f;
;     const bool act = lo == 0 || !SLC;
;     if (NOMASK) {
; #pragma unroll
;         for (int j = 0; j < 8; ++j) { sc[j] = sa[j >> 2][j & 3]; vd[j] = act; }
;         mx = fmaxf(fmaxf(fmaxf(sc[0], sc[1]), fmaxf(sc[2], sc[3])), fmaxf(fmaxf(sc[4], sc[5]), fmaxf(sc[6], sc[7])));
;         mx = act ? mx : -1e30f;
;     } else {
; #pragma unroll
;         for (int T = 0; T < 2; ++T)
; #pragma unroll
;             for (int r = 0; r < 4; ++r) { const int p = pos0 + 16 * T + 4 * kq + r; const bool v = (p >= lo) & (p <= hi); const float x = sa[T][r];
;                 sc[4 * T + r] = x; vd[4 * T + r] = v; mx = v ? fmaxf(mx, x) : mx; }
;     }
;     if (__builtin_amdgcn_ballot_w64(mx > st.m + 4.f) != 0ull) {
;         mx = fmaxf(mx, __shfl_xor(mx, 16)); mx = fmaxf(mx, __shfl_xor(mx, 32));
;         const float mn = fmaxf(st.m, mx), alpha = __builtin_amdgcn_exp2f(st.m - mn); st.m = mn; st.l *= alpha;
; #pragma unroll
;         for (int j = 0; j < 8; ++j) st.o[j] = st.o[j] * alpha;
.LBB0_913:
	s_cmp_lt_i32 s59, s56
	s_cselect_b64 s[10:11], -1, 0
	s_or_b32 s12, s59, 31
	s_cmp_gt_i32 s12, s96
	s_cselect_b64 s[12:13], -1, 0
	s_or_b64 s[10:11], s[10:11], s[12:13]
	s_and_b64 s[10:11], s[10:11], exec
	s_cselect_b32 s10, 0, 2.0
	s_add_i32 s58, s58, 4
	s_or_b32 s14, s10, s59
	s_min_i32 s10, s58, s27
	s_add_i32 s12, s10, s26
	s_lshl_b32 s43, s12, 5
	s_and_b32 s10, s43, 0x3fffffe0
	s_lshr_b32 s50, s10, 4
	s_lshl_b64 s[10:11], s[50:51], 11
	s_and_b32 s50, s12, 0x1ffffff
	s_lshl_b64 s[12:13], s[50:51], 12
	s_cmp_lt_u32 s14, 2.0
	v_lshl_add_u64 v[204:205], v[86:87], 0, s[10:11]
	v_lshl_add_u64 v[202:203], v[88:89], 0, s[12:13]
	s_mov_b64 s[10:11], -1
	v_add_f32_e32 v229, 4.0, v230
	s_cbranch_scc1 .LBB0_917
	v_lshl_add_u64 v[244:245], v[204:205], 0, v[118:119]
	global_load_dwordx4 v[154:157], v[244:245], off
	global_load_dwordx4 v[158:161], v[244:245], off offset:1024
	global_load_dwordx4 v[162:165], v[244:245], off offset:2048
	global_load_dwordx4 v[166:169], v[244:245], off offset:3072
	v_lshl_add_u64 v[246:247], v[202:203], 0, v[118:119]
	global_load_dwordx4 v[106:109], v[246:247], off
	global_load_dwordx4 v[110:113], v[246:247], off offset:1024
	global_load_dwordx4 v[114:117], v[246:247], off offset:2048
	global_load_dwordx4 v[134:137], v[246:247], off offset:3072
	s_waitcnt vmcnt(20)
	v_mfma_f32_16x16x128_f8f6f4 v[2:5], v[186:193], v[78:85], 0
	v_mfma_f32_16x16x128_f8f6f4 v[6:9], v[194:201], v[78:85], 0
	v_mov_b32_e32 v133, v230
	v_mov_b32_e32 v34, v231
	s_nop 8
	v_max3_f32 v0, v2, v3, v4
	v_max3_f32 v12, v5, v6, v7
	v_max3_f32 v0, v0, v8, v9
	v_max_f32_e32 v0, v0, v12
	v_cmp_gt_f32_e32 vcc, v0, v229
	s_cbranch_vccz .LBB0_916
	ds_bpermute_b32 v10, v227, v0
	v_max_f32_e32 v0, v0, v0
	s_waitcnt lgkmcnt(0)
	v_max_f32_e32 v10, v10, v10
	v_max_f32_e32 v0, v0, v10
	ds_bpermute_b32 v10, v226, v0
	s_waitcnt lgkmcnt(0)
	v_max3_f32 v133, v230, v0, v10
	v_sub_f32_e32 v0, v230, v133
	v_exp_f32_e32 v0, v0
	s_nop 0
	v_mul_f32_e32 v34, v231, v0
	v_pk_mul_f32 v[38:39], v[38:39], v[0:1] op_sel_hi:[1,0]
	v_pk_mul_f32 v[36:37], v[36:37], v[0:1] op_sel_hi:[1,0]
	v_pk_mul_f32 v[42:43], v[42:43], v[0:1] op_sel_hi:[1,0]
	v_pk_mul_f32 v[40:41], v[40:41], v[0:1] op_sel_hi:[1,0]
	v_pk_mul_f32 v[46:47], v[46:47], v[0:1] op_sel_hi:[1,0]
	v_pk_mul_f32 v[44:45], v[44:45], v[0:1] op_sel_hi:[1,0]
	v_pk_mul_f32 v[50:51], v[50:51], v[0:1] op_sel_hi:[1,0]
	v_pk_mul_f32 v[48:49], v[48:49], v[0:1] op_sel_hi:[1,0]
	v_pk_mul_f32 v[54:55], v[54:55], v[0:1] op_sel_hi:[1,0]
	v_pk_mul_f32 v[52:53], v[52:53], v[0:1] op_sel_hi:[1,0]
	v_pk_mul_f32 v[58:59], v[58:59], v[0:1] op_sel_hi:[1,0]
	v_pk_mul_f32 v[56:57], v[56:57], v[0:1] op_sel_hi:[1,0]
	v_pk_mul_f32 v[62:63], v[62:63], v[0:1] op_sel_hi:[1,0]
	v_pk_mul_f32 v[60:61], v[60:61], v[0:1] op_sel_hi:[1,0]
	v_pk_mul_f32 v[66:67], v[66:67], v[0:1] op_sel_hi:[1,0]
	v_pk_mul_f32 v[64:65], v[64:65], v[0:1] op_sel_hi:[1,0]

; template <bool SLC, bool NOMASK> ...
;     const int kq = lane >> 4;
;     const int pos0 = SLC ? (dcur & 0xfffff) : dcur;
;     const int lo = SLC ? ((((dcur >> 20) == qi) | ((dcur >> 20) == 4)) ? 0 : (1 << 30)) : lo_in;
;     load_frag8(nxt, KF, VF, SLC ? (dnext & 0xfffff) : dnext, lane);
;     f32x4 sa[2] = {(f32x4){0.f, 0.f, 0.f, 0.f}, (f32x4){0.f, 0.f, 0.f, 0.f}};
; #pragma unroll
;     for (int T = 0; T < 2; ++T)
; #pragma unroll
;         for (int s2 = 0; s2 < 4; ++s2) sa[T] = __builtin_amdgcn_mfma_f32_16x16x32_fp8_fp8(cur.k[T][s2], qf[s2], sa[T], 0, 0, 0);
;     float sc[8]; bool vd[8]; float mx = -1e30f;
;     const bool act = lo == 0 || !SLC;
;     if (NOMASK) {
; #pragma unroll
;         for (int j = 0; j < 8; ++j) { sc[j] = sa[j >> 2][j & 3]; vd[j] = act; }
;         mx = fmaxf(fmaxf(fmaxf(sc[0], sc[1]), fmaxf(sc[2], sc[3])), fmaxf(fmaxf(sc[4], sc[5]), fmaxf(sc[6], sc[7])));
;         mx = act ? mx : -1e30f;
;     } else {
; #pragma unroll
;         for (int T = 0; T < 2; ++T)
; #pragma unroll
;             for (int r = 0; r < 4; ++r) { const int p = pos0 + 16 * T + 4 * kq + r; const bool v = (p >= lo) & (p <= hi); const float x = sa[T][r];
;                 sc[4 * T + r] = x; vd[4 * T + r] = v; mx = v ? fmaxf(mx, x) : mx; }
;     }
;     if (__builtin_amdgcn_ballot_w64(mx > st.m + 4.f) != 0ull) {
;         mx = fmaxf(mx, __shfl_xor(mx, 16)); mx = fmaxf(mx, __shfl_xor(mx, 32));
;         const float mn = fmaxf(st.m, mx), alpha = __builtin_amdgcn_exp2f(st.m - mn); st.m = mn; st.l *= alpha;
; #pragma unroll
;         for (int j = 0; j < 8; ++j) st.o[j] = st.o[j] * alpha;
.LBB0_969:
	s_and_b32 s13, s12, 0xfffffbff
	s_cmp_eq_u32 s13, 4
	s_cselect_b64 s[10:11], -1, 0
	s_lshl_b32 s14, s66, 7
	s_and_b32 s50, s14, 0x7fff800
	v_lshl_add_u64 v[10:11], v[86:87], 0, s[50:51]
	s_and_b32 s50, s14, 0x7fff000
	v_lshl_add_u64 v[246:247], v[10:11], 0, v[120:121]
	global_load_dwordx4 v[186:189], v[246:247], off
	global_load_dwordx4 v[190:193], v[246:247], off offset:1024
	global_load_dwordx4 v[194:197], v[246:247], off offset:2048
	global_load_dwordx4 v[198:201], v[246:247], off offset:3072
	v_lshl_add_u64 v[10:11], v[88:89], 0, s[50:51]
	v_lshl_add_u64 v[244:245], v[10:11], 0, v[120:121]
	global_load_dwordx4 v[170:173], v[244:245], off
	global_load_dwordx4 v[174:177], v[244:245], off offset:1024
	global_load_dwordx4 v[178:181], v[244:245], off offset:2048
	global_load_dwordx4 v[182:185], v[244:245], off offset:3072
	s_waitcnt vmcnt(20)
	v_mfma_f32_16x16x128_f8f6f4 v[2:5], v[138:145], v[78:85], 0
	v_cmp_eq_u32_e32 vcc, s13, v209
	s_or_b64 s[10:11], s[10:11], vcc
	v_mfma_f32_16x16x128_f8f6f4 v[6:9], v[146:153], v[78:85], 0
	v_mov_b32_e32 v133, v203
	s_nop 9
	v_max3_f32 v0, v2, v3, v4
	v_max3_f32 v12, v5, v6, v7
	v_max3_f32 v0, v0, v8, v9
	v_max_f32_e32 v0, v0, v12
	v_cndmask_b32_e64 v34, v220, v0, s[10:11]
	v_cmp_gt_f32_e32 vcc, v34, v204
	v_mov_b32_e32 v0, v202
	s_cbranch_vccz .LBB0_971
	ds_bpermute_b32 v0, v225, v34
	v_max_f32_e32 v10, v34, v34
	s_waitcnt lgkmcnt(0)
	v_max_f32_e32 v0, v0, v0
	v_max_f32_e32 v0, v10, v0
	ds_bpermute_b32 v10, v224, v0
	s_waitcnt lgkmcnt(0)
	v_max3_f32 v0, v202, v0, v10
	v_sub_f32_e32 v10, v202, v0
	v_exp_f32_e32 v34, v10
	s_nop 0
	v_mul_f32_e32 v133, v203, v34
	v_pk_mul_f32 v[66:67], v[66:67], v[34:35] op_sel_hi:[1,0]
	v_pk_mul_f32 v[64:65], v[64:65], v[34:35] op_sel_hi:[1,0]
	v_pk_mul_f32 v[62:63], v[62:63], v[34:35] op_sel_hi:[1,0]
	v_pk_mul_f32 v[60:61], v[60:61], v[34:35] op_sel_hi:[1,0]
	v_pk_mul_f32 v[58:59], v[58:59], v[34:35] op_sel_hi:[1,0]
	v_pk_mul_f32 v[56:57], v[56:57], v[34:35] op_sel_hi:[1,0]
	v_pk_mul_f32 v[54:55], v[54:55], v[34:35] op_sel_hi:[1,0]
	v_pk_mul_f32 v[52:53], v[52:53], v[34:35] op_sel_hi:[1,0]
	v_pk_mul_f32 v[50:51], v[50:51], v[34:35] op_sel_hi:[1,0]
	v_pk_mul_f32 v[48:49], v[48:49], v[34:35] op_sel_hi:[1,0]
	v_pk_mul_f32 v[46:47], v[46:47], v[34:35] op_sel_hi:[1,0]
	v_pk_mul_f32 v[44:45], v[44:45], v[34:35] op_sel_hi:[1,0]
	v_pk_mul_f32 v[42:43], v[42:43], v[34:35] op_sel_hi:[1,0]
	v_pk_mul_f32 v[40:41], v[40:41], v[34:35] op_sel_hi:[1,0]
	v_pk_mul_f32 v[38:39], v[38:39], v[34:35] op_sel_hi:[1,0]
	v_pk_mul_f32 v[36:37], v[36:37], v[34:35] op_sel_hi:[1,0]

; template <bool SLC, bool NOMASK> ...
;     const int kq = lane >> 4;
;     const int pos0 = SLC ? (dcur & 0xfffff) : dcur;
;     const int lo = SLC ? ((((dcur >> 20) == qi) | ((dcur >> 20) == 4)) ? 0 : (1 << 30)) : lo_in;
;     load_frag8(nxt, KF, VF, SLC ? (dnext & 0xfffff) : dnext, lane);
;     f32x4 sa[2] = {(f32x4){0.f, 0.f, 0.f, 0.f}, (f32x4){0.f, 0.f, 0.f, 0.f}};
; #pragma unroll
;     for (int T = 0; T < 2; ++T)
; #pragma unroll
;         for (int s2 = 0; s2 < 4; ++s2) sa[T] = __builtin_amdgcn_mfma_f32_16x16x32_fp8_fp8(cur.k[T][s2], qf[s2], sa[T], 0, 0, 0);
;     float sc[8]; bool vd[8]; float mx = -1e30f;
;     const bool act = lo == 0 || !SLC;
;     if (NOMASK) {
; #pragma unroll
;         for (int j = 0; j < 8; ++j) { sc[j] = sa[j >> 2][j & 3]; vd[j] = act; }
;         mx = fmaxf(fmaxf(fmaxf(sc[0], sc[1]), fmaxf(sc[2], sc[3])), fmaxf(fmaxf(sc[4], sc[5]), fmaxf(sc[6], sc[7])));
;         mx = act ? mx : -1e30f;
;     } else {
; #pragma unroll
;         for (int T = 0; T < 2; ++T)
; #pragma unroll
;             for (int r = 0; r < 4; ++r) { const int p = pos0 + 16 * T + 4 * kq + r; const bool v = (p >= lo) & (p <= hi); const float x = sa[T][r];
;                 sc[4 * T + r] = x; vd[4 * T + r] = v; mx = v ? fmaxf(mx, x) : mx; }
;     }
;     if (__builtin_amdgcn_ballot_w64(mx > st.m + 4.f) != 0ull) {
;         mx = fmaxf(mx, __shfl_xor(mx, 16)); mx = fmaxf(mx, __shfl_xor(mx, 32));
;         const float mn = fmaxf(st.m, mx), alpha = __builtin_amdgcn_exp2f(st.m - mn); st.m = mn; st.l *= alpha;
; #pragma unroll
;         for (int j = 0; j < 8; ++j) st.o[j] = st.o[j] * alpha;
.LBB0_976:
	s_and_b32 s13, s12, 0xfffffbff
	s_cmp_eq_u32 s13, 4
	s_cselect_b64 s[10:11], -1, 0
	s_lshl_b32 s14, s57, 7
	s_and_b32 s50, s14, 0x7fff800
	v_lshl_add_u64 v[44:45], v[86:87], 0, s[50:51]
	s_and_b32 s50, s14, 0x7fff000
	v_lshl_add_u64 v[246:247], v[44:45], 0, v[120:121]
	global_load_dwordx4 v[138:141], v[246:247], off
	global_load_dwordx4 v[142:145], v[246:247], off offset:1024
	global_load_dwordx4 v[146:149], v[246:247], off offset:2048
	global_load_dwordx4 v[150:153], v[246:247], off offset:3072
	v_lshl_add_u64 v[44:45], v[88:89], 0, s[50:51]
	v_lshl_add_u64 v[244:245], v[44:45], 0, v[120:121]
	global_load_dwordx4 v[90:93], v[244:245], off
	global_load_dwordx4 v[94:97], v[244:245], off offset:1024
	global_load_dwordx4 v[98:101], v[244:245], off offset:2048
	global_load_dwordx4 v[102:105], v[244:245], off offset:3072
	s_waitcnt vmcnt(20)
	v_mfma_f32_16x16x128_f8f6f4 v[36:39], v[154:161], v[78:85], 0
	v_cmp_eq_u32_e32 vcc, s13, v209
	s_or_b64 s[10:11], s[10:11], vcc
	v_mfma_f32_16x16x128_f8f6f4 v[40:43], v[162:169], v[78:85], 0
	v_mov_b32_e32 v203, v0
	s_nop 9
	v_max3_f32 v3, v36, v37, v38
	v_max3_f32 v45, v39, v40, v41
	v_max3_f32 v3, v3, v42, v43
	v_max_f32_e32 v3, v3, v45
	v_cndmask_b32_e64 v202, v220, v3, s[10:11]
	v_cmp_gt_f32_e32 vcc, v202, v2
	v_mov_b32_e32 v3, v133
	s_cbranch_vccz .LBB0_978
	ds_bpermute_b32 v3, v225, v202
	v_max_f32_e32 v44, v202, v202
	s_waitcnt lgkmcnt(0)
	v_max_f32_e32 v3, v3, v3
	v_max_f32_e32 v3, v44, v3
	ds_bpermute_b32 v44, v224, v3
	s_waitcnt lgkmcnt(0)
	v_max3_f32 v203, v0, v3, v44
	v_sub_f32_e32 v3, v0, v203
	v_exp_f32_e32 v72, v3
	s_nop 0
	v_mul_f32_e32 v3, v133, v72
	v_pk_mul_f32 v[10:11], v[10:11], v[72:73] op_sel_hi:[1,0]
	v_pk_mul_f32 v[8:9], v[8:9], v[72:73] op_sel_hi:[1,0]
	v_pk_mul_f32 v[14:15], v[14:15], v[72:73] op_sel_hi:[1,0]
	v_pk_mul_f32 v[12:13], v[12:13], v[72:73] op_sel_hi:[1,0]
	v_pk_mul_f32 v[18:19], v[18:19], v[72:73] op_sel_hi:[1,0]
	v_pk_mul_f32 v[16:17], v[16:17], v[72:73] op_sel_hi:[1,0]
	v_pk_mul_f32 v[22:23], v[22:23], v[72:73] op_sel_hi:[1,0]
	v_pk_mul_f32 v[20:21], v[20:21], v[72:73] op_sel_hi:[1,0]
	v_pk_mul_f32 v[26:27], v[26:27], v[72:73] op_sel_hi:[1,0]
	v_pk_mul_f32 v[24:25], v[24:25], v[72:73] op_sel_hi:[1,0]
	v_pk_mul_f32 v[34:35], v[34:35], v[72:73] op_sel_hi:[1,0]
	v_pk_mul_f32 v[32:33], v[32:33], v[72:73] op_sel_hi:[1,0]
	v_pk_mul_f32 v[30:31], v[30:31], v[72:73] op_sel_hi:[1,0]
	v_pk_mul_f32 v[28:29], v[28:29], v[72:73] op_sel_hi:[1,0]
	v_pk_mul_f32 v[6:7], v[6:7], v[72:73] op_sel_hi:[1,0]
	v_pk_mul_f32 v[4:5], v[4:5], v[72:73] op_sel_hi:[1,0]

; template <bool SLC, bool NOMASK> ...
;     const int kq = lane >> 4;
;     const int pos0 = SLC ? (dcur & 0xfffff) : dcur;
;     const int lo = SLC ? ((((dcur >> 20) == qi) | ((dcur >> 20) == 4)) ? 0 : (1 << 30)) : lo_in;
;     load_frag8(nxt, KF, VF, SLC ? (dnext & 0xfffff) : dnext, lane);
;     f32x4 sa[2] = {(f32x4){0.f, 0.f, 0.f, 0.f}, (f32x4){0.f, 0.f, 0.f, 0.f}};
; #pragma unroll
;     for (int T = 0; T < 2; ++T)
; #pragma unroll
;         for (int s2 = 0; s2 < 4; ++s2) sa[T] = __builtin_amdgcn_mfma_f32_16x16x32_fp8_fp8(cur.k[T][s2], qf[s2], sa[T], 0, 0, 0);
;     float sc[8]; bool vd[8]; float mx = -1e30f;
;     const bool act = lo == 0 || !SLC;
;     if (NOMASK) {
; #pragma unroll
;         for (int j = 0; j < 8; ++j) { sc[j] = sa[j >> 2][j & 3]; vd[j] = act; }
;         mx = fmaxf(fmaxf(fmaxf(sc[0], sc[1]), fmaxf(sc[2], sc[3])), fmaxf(fmaxf(sc[4], sc[5]), fmaxf(sc[6], sc[7])));
;         mx = act ? mx : -1e30f;
;     } else {
; #pragma unroll
;         for (int T = 0; T < 2; ++T)
; #pragma unroll
;             for (int r = 0; r < 4; ++r) { const int p = pos0 + 16 * T + 4 * kq + r; const bool v = (p >= lo) & (p <= hi); const float x = sa[T][r];
;                 sc[4 * T + r] = x; vd[4 * T + r] = v; mx = v ? fmaxf(mx, x) : mx; }
;     }
;     if (__builtin_amdgcn_ballot_w64(mx > st.m + 4.f) != 0ull) {
;         mx = fmaxf(mx, __shfl_xor(mx, 16)); mx = fmaxf(mx, __shfl_xor(mx, 32));
;         const float mn = fmaxf(st.m, mx), alpha = __builtin_amdgcn_exp2f(st.m - mn); st.m = mn; st.l *= alpha;
; #pragma unroll
;         for (int j = 0; j < 8; ++j) st.o[j] = st.o[j] * alpha;
; __device__ __forceinline__ void nsa_unit(int unit, const bf16_t* proj, const bf16_t* kc, const bf16_t* vc, const bf16_t* gn, const float* cs, const float* sn, ...
;     ...
;     { auto desc = [&](int i) { return __builtin_amdgcn_readfirstlane(list[i]); };
.LBB0_982:
	s_cmp_lt_u32 s56, s54
	s_cselect_b32 s10, s56, s55
	s_lshl_b32 s10, s10, 2
	s_add_i32 s10, s3, s10
	v_mov_b32_e32 v0, s10
	ds_read_b32 v0, v0 offset:13632
	s_and_b32 s13, s66, 2.0
	s_ashr_i32 s12, s66, 20
	s_mov_b64 s[10:11], -1
	s_cmp_eq_u32 s13, 0
	s_waitcnt lgkmcnt(0)
	v_readfirstlane_b32 s92, v0
	v_add_f32_e32 v0, 4.0, v203
	s_cbranch_scc1 .LBB0_986
	s_and_b32 s13, s12, 0xfffffbff
	s_cmp_eq_u32 s13, 4
	s_cselect_b64 s[10:11], -1, 0
	s_lshl_b32 s14, s92, 7
	s_and_b32 s50, s14, 0x7fff800
	v_lshl_add_u64 v[10:11], v[86:87], 0, s[50:51]
	s_and_b32 s50, s14, 0x7fff000
	v_lshl_add_u64 v[246:247], v[10:11], 0, v[120:121]
	global_load_dwordx4 v[154:157], v[246:247], off
	global_load_dwordx4 v[158:161], v[246:247], off offset:1024
	global_load_dwordx4 v[162:165], v[246:247], off offset:2048
	global_load_dwordx4 v[166:169], v[246:247], off offset:3072
	v_lshl_add_u64 v[10:11], v[88:89], 0, s[50:51]
	v_lshl_add_u64 v[244:245], v[10:11], 0, v[120:121]
	global_load_dwordx4 v[106:109], v[244:245], off
	global_load_dwordx4 v[110:113], v[244:245], off offset:1024
	global_load_dwordx4 v[114:117], v[244:245], off offset:2048
	global_load_dwordx4 v[134:137], v[244:245], off offset:3072
	s_waitcnt vmcnt(20)
	v_mfma_f32_16x16x128_f8f6f4 v[2:5], v[186:193], v[78:85], 0
	v_cmp_eq_u32_e32 vcc, s13, v209
	s_or_b64 s[10:11], s[10:11], vcc
	v_mfma_f32_16x16x128_f8f6f4 v[6:9], v[194:201], v[78:85], 0
	v_mov_b32_e32 v202, v203
	v_mov_b32_e32 v133, v204
	s_nop 8
	v_max3_f32 v10, v2, v3, v4
	v_max3_f32 v12, v5, v6, v7
	v_max3_f32 v10, v10, v8, v9
	v_max_f32_e32 v10, v10, v12
	v_cndmask_b32_e64 v34, v220, v10, s[10:11]
	v_cmp_gt_f32_e32 vcc, v34, v0
	s_cbranch_vccz .LBB0_985
	ds_bpermute_b32 v10, v225, v34
	v_max_f32_e32 v11, v34, v34
	s_waitcnt lgkmcnt(0)
	v_max_f32_e32 v10, v10, v10
	v_max_f32_e32 v10, v11, v10
	ds_bpermute_b32 v11, v224, v10
	s_waitcnt lgkmcnt(0)
	v_max3_f32 v202, v203, v10, v11
	v_sub_f32_e32 v10, v203, v202
	v_exp_f32_e32 v34, v10
	s_nop 0
	v_mul_f32_e32 v133, v204, v34
	v_pk_mul_f32 v[38:39], v[38:39], v[34:35] op_sel_hi:[1,0]
	v_pk_mul_f32 v[36:37], v[36:37], v[34:35] op_sel_hi:[1,0]
	v_pk_mul_f32 v[42:43], v[42:43], v[34:35] op_sel_hi:[1,0]
	v_pk_mul_f32 v[40:41], v[40:41], v[34:35] op_sel_hi:[1,0]
	v_pk_mul_f32 v[46:47], v[46:47], v[34:35] op_sel_hi:[1,0]
	v_pk_mul_f32 v[44:45], v[44:45], v[34:35] op_sel_hi:[1,0]
	v_pk_mul_f32 v[50:51], v[50:51], v[34:35] op_sel_hi:[1,0]
	v_pk_mul_f32 v[48:49], v[48:49], v[34:35] op_sel_hi:[1,0]
	v_pk_mul_f32 v[54:55], v[54:55], v[34:35] op_sel_hi:[1,0]
	v_pk_mul_f32 v[52:53], v[52:53], v[34:35] op_sel_hi:[1,0]
	v_pk_mul_f32 v[58:59], v[58:59], v[34:35] op_sel_hi:[1,0]
	v_pk_mul_f32 v[56:57], v[56:57], v[34:35] op_sel_hi:[1,0]
	v_pk_mul_f32 v[62:63], v[62:63], v[34:35] op_sel_hi:[1,0]
	v_pk_mul_f32 v[60:61], v[60:61], v[34:35] op_sel_hi:[1,0]
	v_pk_mul_f32 v[66:67], v[66:67], v[34:35] op_sel_hi:[1,0]
	v_pk_mul_f32 v[64:65], v[64:65], v[34:35] op_sel_hi:[1,0]

; template <bool SLC, bool NOMASK> ...
;     const int kq = lane >> 4;
;     const int pos0 = SLC ? (dcur & 0xfffff) : dcur;
;     const int lo = SLC ? ((((dcur >> 20) == qi) | ((dcur >> 20) == 4)) ? 0 : (1 << 30)) : lo_in;
;     load_frag8(nxt, KF, VF, SLC ? (dnext & 0xfffff) : dnext, lane);
;     f32x4 sa[2] = {(f32x4){0.f, 0.f, 0.f, 0.f}, (f32x4){0.f, 0.f, 0.f, 0.f}};
; #pragma unroll
;     for (int T = 0; T < 2; ++T)
; #pragma unroll
;         for (int s2 = 0; s2 < 4; ++s2) sa[T] = __builtin_amdgcn_mfma_f32_16x16x32_fp8_fp8(cur.k[T][s2], qf[s2], sa[T], 0, 0, 0);
;     float sc[8]; bool vd[8]; float mx = -1e30f;
;     const bool act = lo == 0 || !SLC;
;     if (NOMASK) {
; #pragma unroll
;         for (int j = 0; j < 8; ++j) { sc[j] = sa[j >> 2][j & 3]; vd[j] = act; }
;         mx = fmaxf(fmaxf(fmaxf(sc[0], sc[1]), fmaxf(sc[2], sc[3])), fmaxf(fmaxf(sc[4], sc[5]), fmaxf(sc[6], sc[7])));
;         mx = act ? mx : -1e30f;
;     } else {
; #pragma unroll
;         for (int T = 0; T < 2; ++T)
; #pragma unroll
;             for (int r = 0; r < 4; ++r) { const int p = pos0 + 16 * T + 4 * kq + r; const bool v = (p >= lo) & (p <= hi); const float x = sa[T][r];
;                 sc[4 * T + r] = x; vd[4 * T + r] = v; mx = v ? fmaxf(mx, x) : mx; }
;     }
;     if (__builtin_amdgcn_ballot_w64(mx > st.m + 4.f) != 0ull) {
;         mx = fmaxf(mx, __shfl_xor(mx, 16)); mx = fmaxf(mx, __shfl_xor(mx, 32));
;         const float mn = fmaxf(st.m, mx), alpha = __builtin_amdgcn_exp2f(st.m - mn); st.m = mn; st.l *= alpha;
; #pragma unroll
;         for (int j = 0; j < 8; ++j) st.o[j] = st.o[j] * alpha;
.LBB0_1002:
	v_lshl_add_u64 v[246:247], v[204:205], 0, v[120:121]
	global_load_dwordx4 v[186:189], v[246:247], off
	global_load_dwordx4 v[190:193], v[246:247], off offset:1024
	global_load_dwordx4 v[194:197], v[246:247], off offset:2048
	global_load_dwordx4 v[198:201], v[246:247], off offset:3072
	v_lshl_add_u64 v[244:245], v[202:203], 0, v[120:121]
	global_load_dwordx4 v[170:173], v[244:245], off
	global_load_dwordx4 v[174:177], v[244:245], off offset:1024
	global_load_dwordx4 v[178:181], v[244:245], off offset:2048
	global_load_dwordx4 v[182:185], v[244:245], off offset:3072
	s_waitcnt vmcnt(20)
	v_mfma_f32_16x16x128_f8f6f4 v[2:5], v[138:145], v[78:85], 0
	v_mfma_f32_16x16x128_f8f6f4 v[6:9], v[146:153], v[78:85], 0
	v_mov_b32_e32 v228, v133
	v_mov_b32_e32 v34, v227
	s_nop 8
	v_max3_f32 v0, v2, v3, v4
	v_max3_f32 v12, v5, v6, v7
	v_max3_f32 v0, v0, v8, v9
	v_max_f32_e32 v0, v0, v12
	v_add_f32_e32 v10, 4.0, v133
	v_cmp_gt_f32_e32 vcc, v0, v10
	s_cbranch_vccz .LBB0_1004
	ds_bpermute_b32 v10, v225, v0
	v_max_f32_e32 v0, v0, v0
	s_waitcnt lgkmcnt(0)
	v_max_f32_e32 v10, v10, v10
	v_max_f32_e32 v0, v0, v10
	ds_bpermute_b32 v10, v224, v0
	s_waitcnt lgkmcnt(0)
	v_max3_f32 v228, v133, v0, v10
	v_sub_f32_e32 v0, v133, v228
	v_exp_f32_e32 v0, v0
	s_nop 0
	v_mul_f32_e32 v34, v227, v0
	v_pk_mul_f32 v[66:67], v[66:67], v[0:1] op_sel_hi:[1,0]
	v_pk_mul_f32 v[64:65], v[64:65], v[0:1] op_sel_hi:[1,0]
	v_pk_mul_f32 v[62:63], v[62:63], v[0:1] op_sel_hi:[1,0]
	v_pk_mul_f32 v[60:61], v[60:61], v[0:1] op_sel_hi:[1,0]
	v_pk_mul_f32 v[58:59], v[58:59], v[0:1] op_sel_hi:[1,0]
	v_pk_mul_f32 v[56:57], v[56:57], v[0:1] op_sel_hi:[1,0]
	v_pk_mul_f32 v[54:55], v[54:55], v[0:1] op_sel_hi:[1,0]
	v_pk_mul_f32 v[52:53], v[52:53], v[0:1] op_sel_hi:[1,0]
	v_pk_mul_f32 v[50:51], v[50:51], v[0:1] op_sel_hi:[1,0]
	v_pk_mul_f32 v[48:49], v[48:49], v[0:1] op_sel_hi:[1,0]
	v_pk_mul_f32 v[46:47], v[46:47], v[0:1] op_sel_hi:[1,0]
	v_pk_mul_f32 v[44:45], v[44:45], v[0:1] op_sel_hi:[1,0]
	v_pk_mul_f32 v[42:43], v[42:43], v[0:1] op_sel_hi:[1,0]
	v_pk_mul_f32 v[40:41], v[40:41], v[0:1] op_sel_hi:[1,0]
	v_pk_mul_f32 v[38:39], v[38:39], v[0:1] op_sel_hi:[1,0]
	v_pk_mul_f32 v[36:37], v[36:37], v[0:1] op_sel_hi:[1,0]

; template <bool SLC, bool NOMASK> ...
;     const int kq = lane >> 4;
;     const int pos0 = SLC ? (dcur & 0xfffff) : dcur;
;     const int lo = SLC ? ((((dcur >> 20) == qi) | ((dcur >> 20) == 4)) ? 0 : (1 << 30)) : lo_in;
;     load_frag8(nxt, KF, VF, SLC ? (dnext & 0xfffff) : dnext, lane);
;     f32x4 sa[2] = {(f32x4){0.f, 0.f, 0.f, 0.f}, (f32x4){0.f, 0.f, 0.f, 0.f}};
; #pragma unroll
;     for (int T = 0; T < 2; ++T)
; #pragma unroll
;         for (int s2 = 0; s2 < 4; ++s2) sa[T] = __builtin_amdgcn_mfma_f32_16x16x32_fp8_fp8(cur.k[T][s2], qf[s2], sa[T], 0, 0, 0);
;     float sc[8]; bool vd[8]; float mx = -1e30f;
;     const bool act = lo == 0 || !SLC;
;     if (NOMASK) {
; #pragma unroll
;         for (int j = 0; j < 8; ++j) { sc[j] = sa[j >> 2][j & 3]; vd[j] = act; }
;         mx = fmaxf(fmaxf(fmaxf(sc[0], sc[1]), fmaxf(sc[2], sc[3])), fmaxf(fmaxf(sc[4], sc[5]), fmaxf(sc[6], sc[7])));
;         mx = act ? mx : -1e30f;
;     } else {
; #pragma unroll
;         for (int T = 0; T < 2; ++T)
; #pragma unroll
;             for (int r = 0; r < 4; ++r) { const int p = pos0 + 16 * T + 4 * kq + r; const bool v = (p >= lo) & (p <= hi); const float x = sa[T][r];
;                 sc[4 * T + r] = x; vd[4 * T + r] = v; mx = v ? fmaxf(mx, x) : mx; }
;     }
;     if (__builtin_amdgcn_ballot_w64(mx > st.m + 4.f) != 0ull) {
;         mx = fmaxf(mx, __shfl_xor(mx, 16)); mx = fmaxf(mx, __shfl_xor(mx, 32));
;         const float mn = fmaxf(st.m, mx), alpha = __builtin_amdgcn_exp2f(st.m - mn); st.m = mn; st.l *= alpha;
; #pragma unroll
;         for (int j = 0; j < 8; ++j) st.o[j] = st.o[j] * alpha;
.LBB0_1009:
	v_lshl_add_u64 v[246:247], v[204:205], 0, v[120:121]
	global_load_dwordx4 v[138:141], v[246:247], off
	global_load_dwordx4 v[142:145], v[246:247], off offset:1024
	global_load_dwordx4 v[146:149], v[246:247], off offset:2048
	global_load_dwordx4 v[150:153], v[246:247], off offset:3072
	v_lshl_add_u64 v[244:245], v[202:203], 0, v[120:121]
	global_load_dwordx4 v[90:93], v[244:245], off
	global_load_dwordx4 v[94:97], v[244:245], off offset:1024
	global_load_dwordx4 v[98:101], v[244:245], off offset:2048
	global_load_dwordx4 v[102:105], v[244:245], off offset:3072
	s_waitcnt vmcnt(20)
	v_mfma_f32_16x16x128_f8f6f4 v[36:39], v[154:161], v[78:85], 0
	v_mfma_f32_16x16x128_f8f6f4 v[40:43], v[162:169], v[78:85], 0
	v_mov_b32_e32 v227, v228
	v_mov_b32_e32 v229, v34
	s_nop 8
	v_max3_f32 v0, v36, v37, v38
	v_max3_f32 v45, v39, v40, v41
	v_max3_f32 v0, v0, v42, v43
	v_max_f32_e32 v0, v0, v45
	v_cmp_gt_f32_e32 vcc, v0, v133
	s_cbranch_vccz .LBB0_1011
	ds_bpermute_b32 v44, v225, v0
	v_max_f32_e32 v0, v0, v0
	s_waitcnt lgkmcnt(0)
	v_max_f32_e32 v44, v44, v44
	v_max_f32_e32 v0, v0, v44
	ds_bpermute_b32 v44, v224, v0
	s_waitcnt lgkmcnt(0)
	v_max3_f32 v227, v228, v0, v44
	v_sub_f32_e32 v0, v228, v227
	v_exp_f32_e32 v0, v0
	s_nop 0
	v_mul_f32_e32 v229, v34, v0
	v_pk_mul_f32 v[8:9], v[8:9], v[0:1] op_sel_hi:[1,0]
	v_pk_mul_f32 v[6:7], v[6:7], v[0:1] op_sel_hi:[1,0]
	v_pk_mul_f32 v[12:13], v[12:13], v[0:1] op_sel_hi:[1,0]
	v_pk_mul_f32 v[10:11], v[10:11], v[0:1] op_sel_hi:[1,0]
	v_pk_mul_f32 v[16:17], v[16:17], v[0:1] op_sel_hi:[1,0]
	v_pk_mul_f32 v[14:15], v[14:15], v[0:1] op_sel_hi:[1,0]
	v_pk_mul_f32 v[20:21], v[20:21], v[0:1] op_sel_hi:[1,0]
	v_pk_mul_f32 v[18:19], v[18:19], v[0:1] op_sel_hi:[1,0]
	v_pk_mul_f32 v[24:25], v[24:25], v[0:1] op_sel_hi:[1,0]
	v_pk_mul_f32 v[22:23], v[22:23], v[0:1] op_sel_hi:[1,0]
	v_pk_mul_f32 v[28:29], v[28:29], v[0:1] op_sel_hi:[1,0]
	v_pk_mul_f32 v[26:27], v[26:27], v[0:1] op_sel_hi:[1,0]
	v_pk_mul_f32 v[32:33], v[32:33], v[0:1] op_sel_hi:[1,0]
	v_pk_mul_f32 v[30:31], v[30:31], v[0:1] op_sel_hi:[1,0]
	v_pk_mul_f32 v[4:5], v[4:5], v[0:1] op_sel_hi:[1,0]
	v_pk_mul_f32 v[2:3], v[2:3], v[0:1] op_sel_hi:[1,0]

; template <bool SLC, bool NOMASK> ...
;     const int kq = lane >> 4;
;     const int pos0 = SLC ? (dcur & 0xfffff) : dcur;
;     const int lo = SLC ? ((((dcur >> 20) == qi) | ((dcur >> 20) == 4)) ? 0 : (1 << 30)) : lo_in;
;     load_frag8(nxt, KF, VF, SLC ? (dnext & 0xfffff) : dnext, lane);
;     f32x4 sa[2] = {(f32x4){0.f, 0.f, 0.f, 0.f}, (f32x4){0.f, 0.f, 0.f, 0.f}};
; #pragma unroll
;     for (int T = 0; T < 2; ++T)
; #pragma unroll
;         for (int s2 = 0; s2 < 4; ++s2) sa[T] = __builtin_amdgcn_mfma_f32_16x16x32_fp8_fp8(cur.k[T][s2], qf[s2], sa[T], 0, 0, 0);
;     float sc[8]; bool vd[8]; float mx = -1e30f;
;     const bool act = lo == 0 || !SLC;
;     if (NOMASK) {
; #pragma unroll
;         for (int j = 0; j < 8; ++j) { sc[j] = sa[j >> 2][j & 3]; vd[j] = act; }
;         mx = fmaxf(fmaxf(fmaxf(sc[0], sc[1]), fmaxf(sc[2], sc[3])), fmaxf(fmaxf(sc[4], sc[5]), fmaxf(sc[6], sc[7])));
;         mx = act ? mx : -1e30f;
;     } else {
; #pragma unroll
;         for (int T = 0; T < 2; ++T)
; #pragma unroll
;             for (int r = 0; r < 4; ++r) { const int p = pos0 + 16 * T + 4 * kq + r; const bool v = (p >= lo) & (p <= hi); const float x = sa[T][r];
;                 sc[4 * T + r] = x; vd[4 * T + r] = v; mx = v ? fmaxf(mx, x) : mx; }
;     }
;     if (__builtin_amdgcn_ballot_w64(mx > st.m + 4.f) != 0ull) {
;         mx = fmaxf(mx, __shfl_xor(mx, 16)); mx = fmaxf(mx, __shfl_xor(mx, 32));
;         const float mn = fmaxf(st.m, mx), alpha = __builtin_amdgcn_exp2f(st.m - mn); st.m = mn; st.l *= alpha;
; #pragma unroll
;         for (int j = 0; j < 8; ++j) st.o[j] = st.o[j] * alpha;
.LBB0_1015:
	s_cmp_lt_i32 s57, s54
	s_cselect_b64 s[10:11], -1, 0
	s_or_b32 s12, s57, 31
	s_cmp_gt_i32 s12, s90
	s_cselect_b64 s[12:13], -1, 0
	s_or_b64 s[10:11], s[10:11], s[12:13]
	s_and_b64 s[10:11], s[10:11], exec
	s_cselect_b32 s10, 0, 2.0
	s_add_i32 s56, s56, 4
	s_or_b32 s14, s10, s57
	s_min_i32 s10, s56, s27
	s_add_i32 s12, s10, s26
	s_lshl_b32 s43, s12, 5
	s_and_b32 s10, s43, 0x3fffffe0
	s_lshr_b32 s50, s10, 4
	s_lshl_b64 s[10:11], s[50:51], 11
	s_and_b32 s50, s12, 0x1ffffff
	s_lshl_b64 s[12:13], s[50:51], 12
	s_cmp_lt_u32 s14, 2.0
	v_lshl_add_u64 v[204:205], v[86:87], 0, s[10:11]
	v_lshl_add_u64 v[202:203], v[88:89], 0, s[12:13]
	s_mov_b64 s[10:11], -1
	v_add_f32_e32 v228, 4.0, v227
	s_cbranch_scc1 .LBB0_1019
	v_lshl_add_u64 v[246:247], v[204:205], 0, v[120:121]
	global_load_dwordx4 v[154:157], v[246:247], off
	global_load_dwordx4 v[158:161], v[246:247], off offset:1024
	global_load_dwordx4 v[162:165], v[246:247], off offset:2048
	global_load_dwordx4 v[166:169], v[246:247], off offset:3072
	v_lshl_add_u64 v[244:245], v[202:203], 0, v[120:121]
	global_load_dwordx4 v[106:109], v[244:245], off
	global_load_dwordx4 v[110:113], v[244:245], off offset:1024
	global_load_dwordx4 v[114:117], v[244:245], off offset:2048
	global_load_dwordx4 v[134:137], v[244:245], off offset:3072
	s_waitcnt vmcnt(20)
	v_mfma_f32_16x16x128_f8f6f4 v[2:5], v[186:193], v[78:85], 0
	v_mfma_f32_16x16x128_f8f6f4 v[6:9], v[194:201], v[78:85], 0
	v_mov_b32_e32 v133, v227
	v_mov_b32_e32 v34, v229
	s_nop 8
	v_max3_f32 v0, v2, v3, v4
	v_max3_f32 v12, v5, v6, v7
	v_max3_f32 v0, v0, v8, v9
	v_max_f32_e32 v0, v0, v12
	v_cmp_gt_f32_e32 vcc, v0, v228
	s_cbranch_vccz .LBB0_1018
	ds_bpermute_b32 v10, v225, v0
	v_max_f32_e32 v0, v0, v0
	s_waitcnt lgkmcnt(0)
	v_max_f32_e32 v10, v10, v10
	v_max_f32_e32 v0, v0, v10
	ds_bpermute_b32 v10, v224, v0
	s_waitcnt lgkmcnt(0)
	v_max3_f32 v133, v227, v0, v10
	v_sub_f32_e32 v0, v227, v133
	v_exp_f32_e32 v0, v0
	s_nop 0
	v_mul_f32_e32 v34, v229, v0
	v_pk_mul_f32 v[38:39], v[38:39], v[0:1] op_sel_hi:[1,0]
	v_pk_mul_f32 v[36:37], v[36:37], v[0:1] op_sel_hi:[1,0]
	v_pk_mul_f32 v[42:43], v[42:43], v[0:1] op_sel_hi:[1,0]
	v_pk_mul_f32 v[40:41], v[40:41], v[0:1] op_sel_hi:[1,0]
	v_pk_mul_f32 v[46:47], v[46:47], v[0:1] op_sel_hi:[1,0]
	v_pk_mul_f32 v[44:45], v[44:45], v[0:1] op_sel_hi:[1,0]
	v_pk_mul_f32 v[50:51], v[50:51], v[0:1] op_sel_hi:[1,0]
	v_pk_mul_f32 v[48:49], v[48:49], v[0:1] op_sel_hi:[1,0]
	v_pk_mul_f32 v[54:55], v[54:55], v[0:1] op_sel_hi:[1,0]
	v_pk_mul_f32 v[52:53], v[52:53], v[0:1] op_sel_hi:[1,0]
	v_pk_mul_f32 v[58:59], v[58:59], v[0:1] op_sel_hi:[1,0]
	v_pk_mul_f32 v[56:57], v[56:57], v[0:1] op_sel_hi:[1,0]
	v_pk_mul_f32 v[62:63], v[62:63], v[0:1] op_sel_hi:[1,0]
	v_pk_mul_f32 v[60:61], v[60:61], v[0:1] op_sel_hi:[1,0]
	v_pk_mul_f32 v[66:67], v[66:67], v[0:1] op_sel_hi:[1,0]
	v_pk_mul_f32 v[64:65], v[64:65], v[0:1] op_sel_hi:[1,0]
